# replace butterfly ds_bpermute round trips by DPP adds and permlane16/32 swaps in conv, fused GEMM epilogues and prologue row-norm (stacked on hoists + peel)
# speedup vs baseline: 1.0250x; 1.0044x over previous
.LBB0_126:
	v_add_co_u32_e32 v18, vcc, 0xffffd000, v68
	s_nop 1
	v_addc_co_u32_e32 v19, vcc, -1, v69, vcc
	global_load_dwordx4 v[62:65], v[18:19], off offset:-3072
	global_load_dwordx4 v[58:61], v[18:19], off offset:-2048
	global_load_dwordx4 v[54:57], v[18:19], off offset:-1024
	global_load_dwordx4 v[46:49], v[18:19], off
	global_load_dwordx4 v[6:9], v[68:69], off offset:-3072
	global_load_dwordx4 v[2:5], v[68:69], off offset:-2048
	global_load_dwordx4 v[14:17], v[68:69], off offset:-1024
	global_load_dwordx4 v[10:13], v[68:69], off
	v_add_co_u32_e32 v18, vcc, 0xffffe000, v68
	s_waitcnt vmcnt(7)
	v_mul_f32_e32 v66, v63, v63
	v_addc_co_u32_e32 v19, vcc, -1, v69, vcc
	v_add_co_u32_e32 v80, vcc, 0xfffff000, v68
	global_load_dwordx4 v[50:53], v[18:19], off offset:-3072
	global_load_dwordx4 v[42:45], v[18:19], off offset:-2048
	global_load_dwordx4 v[38:41], v[18:19], off offset:-1024
	global_load_dwordx4 v[34:37], v[18:19], off
	v_addc_co_u32_e32 v81, vcc, -1, v69, vcc
	global_load_dwordx4 v[30:33], v[80:81], off offset:-3072
	global_load_dwordx4 v[26:29], v[80:81], off offset:-2048
	s_waitcnt lgkmcnt(0)
	global_load_dwordx4 v[22:25], v[80:81], off offset:-1024
	global_load_dwordx4 v[18:21], v[68:69], off offset:-4096
	v_mul_f32_e32 v71, v65, v65
	s_waitcnt vmcnt(14)
	v_mul_f32_e32 v80, v59, v59
	v_mul_f32_e32 v81, v61, v61
	s_waitcnt vmcnt(13)
	v_mul_f32_e32 v82, v55, v55
	v_mul_f32_e32 v83, v57, v57
	v_fmac_f32_e32 v66, v62, v62
	v_fmac_f32_e32 v71, v64, v64
	v_fmac_f32_e32 v80, v58, v58
	v_fmac_f32_e32 v81, v60, v60
	s_waitcnt vmcnt(12)
	v_mul_f32_e32 v84, v47, v47
	v_mul_f32_e32 v85, v49, v49
	v_fmac_f32_e32 v82, v54, v54
	v_fmac_f32_e32 v83, v56, v56
	v_add_f32_e32 v66, v66, v71
	v_add_f32_e32 v71, v80, v81
	v_fmac_f32_e32 v84, v46, v46
	v_fmac_f32_e32 v85, v48, v48
	v_add_f32_e32 v80, v82, v83
	v_add_f32_e32 v66, v66, v71
	v_add_f32_e32 v81, v84, v85
	v_add_f32_e32 v66, v66, v80
	v_add_f32_e32 v66, v66, v81
	s_waitcnt lgkmcnt(0)
	s_nop 1
	v_add_f32_dpp v66, v66, v66 quad_perm:[1,0,3,2] row_mask:0xf bank_mask:0xf
	s_waitcnt lgkmcnt(0)
	s_nop 1
	v_add_f32_dpp v66, v66, v66 quad_perm:[2,3,0,1] row_mask:0xf bank_mask:0xf
	s_waitcnt lgkmcnt(0)
	s_nop 1
	v_add_f32_dpp v66, v66, v66 row_half_mirror row_mask:0xf bank_mask:0xf
	s_waitcnt lgkmcnt(0)
	s_nop 1
	v_add_f32_dpp v66, v66, v66 row_mirror row_mask:0xf bank_mask:0xf
	s_nop 1
	v_mov_b32_e32 v71, v66
	s_nop 1
	v_permlane16_swap_b32_e32 v71, v66
	s_waitcnt lgkmcnt(0)
	v_add_f32_e32 v66, v66, v71
	s_nop 1
	v_mov_b32_e32 v71, v66
	s_nop 1
	v_permlane32_swap_b32_e32 v71, v66
	s_and_saveexec_b64 s[20:21], s[4:5]
	s_cbranch_execz .LBB0_128
	s_waitcnt lgkmcnt(0)
	v_add_f32_e32 v66, v66, v71
	v_fmamk_f32 v66, v66, 0x3a800000, v1
	v_mul_f32_e32 v71, 0x4b800000, v66
	v_cmp_gt_f32_e32 vcc, s7, v66
	s_nop 1
	v_cndmask_b32_e32 v66, v66, v71, vcc
	v_rsq_f32_e32 v66, v66
	s_nop 0
	v_mul_f32_e32 v71, 0x45800000, v66
	v_cndmask_b32_e32 v66, v66, v71, vcc
	global_store_dword v67, v66, s[14:15] offset:-12
.LBB0_128:
	s_or_b64 exec, exec, s[20:21]
	s_ashr_i32 s9, s6, 5
	v_cvt_pk_bf16_f32 v80, v62, v63
	v_cvt_pk_bf16_f32 v81, v64, v65
	v_and_or_b32 v64, s9, -8, v78
	s_and_b32 s13, s6, 0xfc
	v_ashrrev_i32_e32 v65, 31, v64
	v_lshlrev_b64 v[62:63], 16, v[64:65]
	v_or_b32_e32 v65, s13, v79
	v_lshl_add_u64 v[62:63], s[2:3], 0, v[62:63]
	v_lshlrev_b32_e32 v66, 6, v65
	v_lshl_add_u64 v[62:63], v[62:63], 0, v[66:67]
	s_waitcnt lgkmcnt(0)
	v_mov_b32_e32 v71, v67
	v_lshl_add_u64 v[62:63], v[62:63], 0, v[70:71]
	global_store_dwordx2 v[62:63], v[80:81], off
	v_cvt_pk_bf16_f32 v80, v58, v59
	v_cvt_pk_bf16_f32 v81, v60, v61
	s_waitcnt vmcnt(8)
	v_mul_f32_e32 v59, v51, v51
	v_mul_f32_e32 v60, v53, v53
	v_fmac_f32_e32 v59, v50, v50
	v_fmac_f32_e32 v60, v52, v52
	v_add_f32_e32 v59, v59, v60
	s_waitcnt vmcnt(7)
	v_mul_f32_e32 v60, v43, v43
	v_mul_f32_e32 v61, v45, v45
	v_fmac_f32_e32 v60, v42, v42
	v_fmac_f32_e32 v61, v44, v44
	v_add_f32_e32 v60, v60, v61
	v_add_f32_e32 v59, v59, v60
	s_waitcnt vmcnt(6)
	v_mul_f32_e32 v60, v39, v39
	v_mul_f32_e32 v61, v41, v41
	v_fmac_f32_e32 v60, v38, v38
	v_fmac_f32_e32 v61, v40, v40
	v_add_f32_e32 v60, v60, v61
	v_add_f32_e32 v59, v59, v60
	s_waitcnt vmcnt(5)
	v_mul_f32_e32 v60, v35, v35
	v_mul_f32_e32 v61, v37, v37
	v_fmac_f32_e32 v60, v34, v34
	v_fmac_f32_e32 v61, v36, v36
	v_add_f32_e32 v60, v60, v61
	v_add_f32_e32 v60, v59, v60
	v_or_b32_e32 v58, 2, v64
	v_ashrrev_i32_e32 v59, 31, v58
	v_lshlrev_b64 v[58:59], 16, v[58:59]
	v_lshl_add_u64 v[58:59], s[2:3], 0, v[58:59]
	s_waitcnt lgkmcnt(0)
	s_nop 1
	v_add_f32_dpp v65, v60, v60 quad_perm:[1,0,3,2] row_mask:0xf bank_mask:0xf
	v_lshl_add_u64 v[58:59], v[58:59], 0, v[66:67]
	v_lshl_add_u64 v[58:59], v[58:59], 0, v[70:71]
	global_store_dwordx2 v[58:59], v[80:81], off
	v_cvt_pk_bf16_f32 v60, v54, v55
	v_cvt_pk_bf16_f32 v61, v56, v57
	s_waitcnt lgkmcnt(0)
	s_nop 1
	v_add_f32_dpp v56, v65, v65 quad_perm:[2,3,0,1] row_mask:0xf bank_mask:0xf
	v_or_b32_e32 v54, 4, v64
	v_ashrrev_i32_e32 v55, 31, v54
	v_lshlrev_b64 v[54:55], 16, v[54:55]
	v_lshl_add_u64 v[54:55], s[2:3], 0, v[54:55]
	s_waitcnt lgkmcnt(0)
	s_nop 1
	v_add_f32_dpp v57, v56, v56 row_half_mirror row_mask:0xf bank_mask:0xf
	v_lshl_add_u64 v[54:55], v[54:55], 0, v[66:67]
	v_lshl_add_u64 v[54:55], v[54:55], 0, v[70:71]
	global_store_dwordx2 v[54:55], v[60:61], off
	v_cvt_pk_bf16_f32 v56, v46, v47
	s_waitcnt lgkmcnt(0)
	s_nop 1
	v_add_f32_dpp v60, v57, v57 row_mirror row_mask:0xf bank_mask:0xf
	s_nop 1
	v_mov_b32_e32 v61, v60
	s_nop 1
	v_permlane16_swap_b32_e32 v61, v60
	v_cvt_pk_bf16_f32 v57, v48, v49
	v_or_b32_e32 v46, 6, v64
	v_ashrrev_i32_e32 v47, 31, v46
	v_lshlrev_b64 v[46:47], 16, v[46:47]
	s_waitcnt lgkmcnt(0)
	v_add_f32_e32 v48, v60, v61
	s_nop 1
	v_mov_b32_e32 v49, v48
	s_nop 1
	v_permlane32_swap_b32_e32 v49, v48
	v_lshl_add_u64 v[46:47], s[2:3], 0, v[46:47]
	v_lshl_add_u64 v[46:47], v[46:47], 0, v[66:67]
	v_lshl_add_u64 v[46:47], v[46:47], 0, v[70:71]
	global_store_dwordx2 v[46:47], v[56:57], off
	s_and_saveexec_b64 s[20:21], s[4:5]
	s_cbranch_execz .LBB0_130
	s_waitcnt lgkmcnt(0)
	v_add_f32_e32 v48, v48, v49
	v_fmamk_f32 v48, v48, 0x3a800000, v1
	v_mul_f32_e32 v49, 0x4b800000, v48
	v_cmp_gt_f32_e32 vcc, s7, v48
	s_nop 1
	v_cndmask_b32_e32 v48, v48, v49, vcc
	v_rsq_f32_e32 v48, v48
	s_nop 0
	v_mul_f32_e32 v49, 0x45800000, v48
	v_cndmask_b32_e32 v48, v48, v49, vcc
	global_store_dword v67, v48, s[14:15] offset:-8
.LBB0_130:
	s_or_b64 exec, exec, s[20:21]
	s_waitcnt vmcnt(7)
	v_mul_f32_e32 v48, v31, v31
	s_waitcnt lgkmcnt(0)
	v_mul_f32_e32 v49, v33, v33
	v_fmac_f32_e32 v48, v30, v30
	v_fmac_f32_e32 v49, v32, v32
	v_add_f32_e32 v48, v48, v49
	s_waitcnt vmcnt(6)
	v_mul_f32_e32 v49, v27, v27
	v_mul_f32_e32 v56, v29, v29
	v_fmac_f32_e32 v49, v26, v26
	v_fmac_f32_e32 v56, v28, v28
	v_add_f32_e32 v49, v49, v56
	v_add_f32_e32 v48, v48, v49
	s_waitcnt vmcnt(5)
	v_mul_f32_e32 v49, v23, v23
	v_mul_f32_e32 v56, v25, v25
	v_fmac_f32_e32 v49, v22, v22
	v_fmac_f32_e32 v56, v24, v24
	v_add_f32_e32 v49, v49, v56
	v_add_f32_e32 v48, v48, v49
	s_waitcnt vmcnt(4)
	v_mul_f32_e32 v49, v19, v19
	v_mul_f32_e32 v56, v21, v21
	v_fmac_f32_e32 v49, v18, v18
	v_fmac_f32_e32 v56, v20, v20
	v_add_f32_e32 v49, v49, v56
	v_add_f32_e32 v48, v48, v49
	s_waitcnt lgkmcnt(0)
	s_nop 1
	v_add_f32_dpp v48, v48, v48 quad_perm:[1,0,3,2] row_mask:0xf bank_mask:0xf
	s_waitcnt lgkmcnt(0)
	s_nop 1
	v_add_f32_dpp v48, v48, v48 quad_perm:[2,3,0,1] row_mask:0xf bank_mask:0xf
	s_waitcnt lgkmcnt(0)
	s_nop 1
	v_add_f32_dpp v56, v48, v48 row_half_mirror row_mask:0xf bank_mask:0xf
	v_cvt_pk_bf16_f32 v48, v50, v51
	v_cvt_pk_bf16_f32 v49, v52, v53
	global_store_dwordx2 v[62:63], v[48:49], off offset:64
	v_cvt_pk_bf16_f32 v42, v42, v43
	s_waitcnt lgkmcnt(0)
	s_nop 1
	v_add_f32_dpp v48, v56, v56 row_mirror row_mask:0xf bank_mask:0xf
	s_nop 1
	v_mov_b32_e32 v49, v48
	s_nop 1
	v_permlane16_swap_b32_e32 v49, v48
	v_cvt_pk_bf16_f32 v43, v44, v45
	global_store_dwordx2 v[58:59], v[42:43], off offset:64
	v_cvt_pk_bf16_f32 v42, v38, v39
	v_cvt_pk_bf16_f32 v43, v40, v41
	s_waitcnt lgkmcnt(0)
	v_add_f32_e32 v38, v48, v49
	s_nop 1
	v_mov_b32_e32 v39, v38
	s_nop 1
	v_permlane32_swap_b32_e32 v39, v38
	global_store_dwordx2 v[54:55], v[42:43], off offset:64
	v_cvt_pk_bf16_f32 v34, v34, v35
	v_cvt_pk_bf16_f32 v35, v36, v37
	global_store_dwordx2 v[46:47], v[34:35], off offset:64
	s_and_saveexec_b64 s[20:21], s[4:5]
	s_cbranch_execz .LBB0_132
	s_waitcnt lgkmcnt(0)
	v_add_f32_e32 v34, v38, v39
	v_fmamk_f32 v34, v34, 0x3a800000, v1
	v_mul_f32_e32 v35, 0x4b800000, v34
	v_cmp_gt_f32_e32 vcc, s7, v34
	s_nop 1
	v_cndmask_b32_e32 v34, v34, v35, vcc
	v_rsq_f32_e32 v34, v34
	s_nop 0
	v_mul_f32_e32 v35, 0x45800000, v34
	v_cndmask_b32_e32 v34, v34, v35, vcc
	global_store_dword v67, v34, s[14:15] offset:-4
.LBB0_132:
	s_or_b64 exec, exec, s[20:21]
	v_mul_f32_e32 v34, v7, v7
	v_mul_f32_e32 v35, v9, v9
	v_fmac_f32_e32 v34, v6, v6
	v_fmac_f32_e32 v35, v8, v8
	v_add_f32_e32 v34, v34, v35
	v_mul_f32_e32 v35, v3, v3
	v_mul_f32_e32 v36, v5, v5
	v_fmac_f32_e32 v35, v2, v2
	v_fmac_f32_e32 v36, v4, v4
	v_add_f32_e32 v35, v35, v36
	v_add_f32_e32 v34, v34, v35
	v_mul_f32_e32 v35, v15, v15
	v_mul_f32_e32 v36, v17, v17
	v_fmac_f32_e32 v35, v14, v14
	v_fmac_f32_e32 v36, v16, v16
	v_add_f32_e32 v35, v35, v36
	v_add_f32_e32 v34, v34, v35
	v_mul_f32_e32 v35, v11, v11
	v_mul_f32_e32 v36, v13, v13
	v_fmac_f32_e32 v35, v10, v10
	v_fmac_f32_e32 v36, v12, v12
	v_add_f32_e32 v35, v35, v36
	v_add_f32_e32 v34, v34, v35
	v_cvt_pk_bf16_f32 v30, v30, v31
	v_cvt_pk_bf16_f32 v31, v32, v33
	global_store_dwordx2 v[62:63], v[30:31], off offset:128
	v_cvt_pk_bf16_f32 v26, v26, v27
	s_waitcnt lgkmcnt(0)
	s_nop 1
	v_add_f32_dpp v34, v34, v34 quad_perm:[1,0,3,2] row_mask:0xf bank_mask:0xf
	v_cvt_pk_bf16_f32 v27, v28, v29
	global_store_dwordx2 v[58:59], v[26:27], off offset:128
	v_cvt_pk_bf16_f32 v26, v22, v23
	v_cvt_pk_bf16_f32 v27, v24, v25
	s_waitcnt lgkmcnt(0)
	s_nop 1
	v_add_f32_dpp v34, v34, v34 quad_perm:[2,3,0,1] row_mask:0xf bank_mask:0xf
	global_store_dwordx2 v[54:55], v[26:27], off offset:128
	v_cvt_pk_bf16_f32 v18, v18, v19
	v_cvt_pk_bf16_f32 v19, v20, v21
	global_store_dwordx2 v[46:47], v[18:19], off offset:128
	s_waitcnt lgkmcnt(0)
	s_nop 1
	v_add_f32_dpp v34, v34, v34 row_half_mirror row_mask:0xf bank_mask:0xf
	s_waitcnt lgkmcnt(0)
	s_nop 1
	v_add_f32_dpp v30, v34, v34 row_mirror row_mask:0xf bank_mask:0xf
	s_nop 1
	v_mov_b32_e32 v31, v30
	s_nop 1
	v_permlane16_swap_b32_e32 v31, v30
	s_waitcnt lgkmcnt(0)
	v_add_f32_e32 v22, v30, v31
	s_nop 1
	v_mov_b32_e32 v23, v22
	s_nop 1
	v_permlane32_swap_b32_e32 v23, v22
	s_and_saveexec_b64 s[20:21], s[4:5]
	s_cbranch_execz .LBB0_125
	s_waitcnt lgkmcnt(0)
	v_add_f32_e32 v18, v22, v23
	v_fmamk_f32 v18, v18, 0x3a800000, v1
	v_mul_f32_e32 v19, 0x4b800000, v18
	v_cmp_gt_f32_e32 vcc, s7, v18
	s_nop 1
	v_cndmask_b32_e32 v18, v18, v19, vcc
	v_rsq_f32_e32 v18, v18
	s_nop 0
	v_mul_f32_e32 v19, 0x45800000, v18
	v_cndmask_b32_e32 v18, v18, v19, vcc
	global_store_dword v67, v18, s[14:15]
	s_branch .LBB0_125

.LBB0_227:
	s_lshl_b32 s0, s2, 4
	v_or_b32_e32 v86, s0, v102
	v_mad_i64_i32 v[24:25], s[18:19], v86, s6, v[56:57]
	v_add_co_u32_e32 v26, vcc, 0x1000, v24
	global_load_dwordx4 v[52:55], v[24:25], off
	global_load_dwordx4 v[48:51], v[24:25], off offset:3584
	v_addc_co_u32_e32 v27, vcc, 0, v25, vcc
	global_load_dwordx4 v[44:47], v[26:27], off offset:3072
	v_add_co_u32_e32 v26, vcc, s15, v24
	s_bfe_i32 s0, s2, 0x1001b
	s_nop 0
	v_addc_co_u32_e32 v27, vcc, 0, v25, vcc
	global_load_dwordx4 v[40:43], v[26:27], off offset:2560
	v_add_co_u32_e32 v26, vcc, s35, v24
	v_ashrrev_i32_e32 v87, 31, v86
	s_nop 0
	v_addc_co_u32_e32 v27, vcc, 0, v25, vcc
	global_load_dwordx4 v[36:39], v[26:27], off offset:2048
	v_add_co_u32_e32 v26, vcc, s44, v24
	s_lshr_b32 s0, s0, 19
	s_nop 0
	v_addc_co_u32_e32 v27, vcc, 0, v25, vcc
	v_lshlrev_b64 v[84:85], 11, v[86:87]
	global_load_dwordx4 v[32:35], v[26:27], off offset:1536
	v_add_co_u32_e32 v26, vcc, s46, v24
	v_add_u32_e32 v87, s0, v86
	s_nop 0
	v_addc_co_u32_e32 v27, vcc, 0, v25, vcc
	v_and_b32_e32 v87, 0xffffe000, v87
	v_add_co_u32_e32 v24, vcc, s45, v24
	v_sub_u32_e32 v87, v86, v87
	s_nop 0
	v_addc_co_u32_e32 v25, vcc, 0, v25, vcc
	v_add_u32_e32 v88, -1, v87
	v_cmp_gt_u32_e32 vcc, s15, v88
	v_max_i32_e32 v88, 1, v86
	v_add_u32_e32 v88, -1, v88
	v_min_u32_e32 v88, 0xffff, v88
	v_mul_u32_u24_e32 v208, 0xe00, v88
	v_lshl_add_u64 v[92:93], v[56:57], 0, v[208:209]
	global_load_dwordx4 v[28:31], v[26:27], off offset:1024
	v_lshl_add_u64 v[84:85], v[58:59], 0, v[84:85]
	global_load_dwordx4 v[24:27], v[24:25], off offset:512
	s_nop 0
	global_load_dwordx4 v[88:91], v[92:93], off offset:512
	s_nop 0
	global_load_dwordx4 v[92:95], v[92:93], off offset:1024
	s_add_i32 s2, s2, s3
	s_cmpk_lt_i32 s2, 0x1000
	s_waitcnt vmcnt(1)
	v_cndmask_b32_e32 v97, 0, v88, vcc
	v_or_b32_e32 v88, 1, v86
	v_max_i32_e32 v88, 1, v88
	v_add_u32_e32 v88, -1, v88
	v_min_u32_e32 v88, 0xffff, v88
	v_mul_u32_u24_e32 v208, 0xe00, v88
	s_waitcnt vmcnt(0)
	v_cndmask_b32_e32 v149, 0, v93, vcc
	v_cndmask_b32_e32 v98, 0, v92, vcc
	v_lshl_add_u64 v[92:93], v[56:57], 0, v[208:209]
	v_cndmask_b32_e32 v141, 0, v91, vcc
	v_cndmask_b32_e32 v143, 0, v90, vcc
	v_cndmask_b32_e32 v96, 0, v89, vcc
	v_cndmask_b32_e32 v145, 0, v95, vcc
	v_cndmask_b32_e32 v147, 0, v94, vcc
	global_load_dwordx4 v[88:91], v[92:93], off offset:512
	s_nop 0
	global_load_dwordx4 v[92:95], v[92:93], off offset:1024
	v_cmp_lt_i32_e32 vcc, -1, v87
	v_add_u32_e32 v87, 8, v87
	v_and_b32_e32 v186, 0xffff0000, v145
	s_waitcnt vmcnt(1)
	v_cndmask_b32_e32 v146, 0, v88, vcc
	v_or_b32_e32 v88, 2, v86
	v_max_i32_e32 v88, 1, v88
	v_add_u32_e32 v88, -1, v88
	v_min_u32_e32 v88, 0xffff, v88
	v_mul_u32_u24_e32 v208, 0xe00, v88
	s_waitcnt vmcnt(0)
	v_cndmask_b32_e32 v152, 0, v93, vcc
	v_cndmask_b32_e32 v144, 0, v92, vcc
	v_lshl_add_u64 v[92:93], v[56:57], 0, v[208:209]
	v_cndmask_b32_e32 v99, 0, v91, vcc
	v_cndmask_b32_e32 v100, 0, v90, vcc
	v_cndmask_b32_e32 v101, 0, v89, vcc
	v_cndmask_b32_e32 v151, 0, v95, vcc
	v_cndmask_b32_e32 v153, 0, v94, vcc
	global_load_dwordx4 v[88:91], v[92:93], off offset:512
	s_nop 0
	global_load_dwordx4 v[92:95], v[92:93], off offset:1024
	v_lshlrev_b32_e32 v150, 16, v101
	v_and_b32_e32 v154, 0xffff0000, v101
	v_lshlrev_b32_e32 v158, 16, v100
	v_and_b32_e32 v162, 0xffff0000, v100
	v_lshlrev_b32_e32 v166, 16, v99
	v_and_b32_e32 v170, 0xffff0000, v99
	v_lshlrev_b32_e32 v140, 16, v144
	v_lshlrev_b32_e32 v142, 16, v146
	v_and_b32_e32 v144, 0xffff0000, v144
	v_and_b32_e32 v146, 0xffff0000, v146
	v_lshlrev_b32_e32 v148, 16, v152
	v_and_b32_e32 v152, 0xffff0000, v152
	v_lshlrev_b32_e32 v156, 16, v153
	v_and_b32_e32 v160, 0xffff0000, v153
	v_lshlrev_b32_e32 v164, 16, v151
	v_and_b32_e32 v168, 0xffff0000, v151
	s_waitcnt vmcnt(1)
	v_cndmask_b32_e32 v161, 0, v88, vcc
	v_or_b32_e32 v88, 3, v86
	v_max_i32_e32 v88, 1, v88
	v_add_u32_e32 v88, -1, v88
	v_min_u32_e32 v88, 0xffff, v88
	v_mul_u32_u24_e32 v208, 0xe00, v88
	s_waitcnt vmcnt(0)
	v_cndmask_b32_e32 v167, 0, v93, vcc
	v_cndmask_b32_e32 v169, 0, v92, vcc
	v_lshl_add_u64 v[92:93], v[56:57], 0, v[208:209]
	v_cndmask_b32_e32 v155, 0, v91, vcc
	v_cndmask_b32_e32 v157, 0, v90, vcc
	v_cndmask_b32_e32 v159, 0, v89, vcc
	v_cndmask_b32_e32 v163, 0, v95, vcc
	v_cndmask_b32_e32 v165, 0, v94, vcc
	global_load_dwordx4 v[88:91], v[92:93], off offset:512
	s_nop 0
	global_load_dwordx4 v[92:95], v[92:93], off offset:1024
	v_and_b32_e32 v187, 0xffff0000, v163
	s_waitcnt vmcnt(1)
	v_cndmask_b32_e32 v190, 0, v88, vcc
	v_or_b32_e32 v88, 4, v86
	v_max_i32_e32 v88, 1, v88
	v_add_u32_e32 v88, -1, v88
	v_min_u32_e32 v88, 0xffff, v88
	v_mul_u32_u24_e32 v208, 0xe00, v88
	s_waitcnt vmcnt(0)
	v_cndmask_b32_e32 v193, 0, v93, vcc
	v_cndmask_b32_e32 v194, 0, v92, vcc
	v_lshl_add_u64 v[92:93], v[56:57], 0, v[208:209]
	v_cndmask_b32_e32 v171, 0, v91, vcc
	v_cndmask_b32_e32 v188, 0, v90, vcc
	v_cndmask_b32_e32 v189, 0, v89, vcc
	v_cndmask_b32_e32 v191, 0, v95, vcc
	v_cndmask_b32_e32 v192, 0, v94, vcc
	global_load_dwordx4 v[88:91], v[92:93], off offset:512
	s_nop 0
	global_load_dwordx4 v[92:95], v[92:93], off offset:1024
	v_lshlrev_b32_e32 v151, 16, v189
	v_and_b32_e32 v153, 0xffff0000, v193
	s_waitcnt vmcnt(1)
	v_cndmask_b32_e32 v198, 0, v88, vcc
	v_or_b32_e32 v88, 5, v86
	v_max_i32_e32 v88, 1, v88
	v_add_u32_e32 v88, -1, v88
	v_min_u32_e32 v88, 0xffff, v88
	v_mul_u32_u24_e32 v208, 0xe00, v88
	s_waitcnt vmcnt(0)
	v_cndmask_b32_e32 v201, 0, v93, vcc
	v_cndmask_b32_e32 v202, 0, v92, vcc
	v_lshl_add_u64 v[92:93], v[56:57], 0, v[208:209]
	v_cndmask_b32_e32 v195, 0, v91, vcc
	v_cndmask_b32_e32 v196, 0, v90, vcc
	v_cndmask_b32_e32 v197, 0, v89, vcc
	v_cndmask_b32_e32 v199, 0, v95, vcc
	v_cndmask_b32_e32 v200, 0, v94, vcc
	global_load_dwordx4 v[88:91], v[92:93], off offset:512
	s_nop 0
	global_load_dwordx4 v[92:95], v[92:93], off offset:1024
	s_waitcnt vmcnt(1)
	v_cndmask_b32_e32 v206, 0, v88, vcc
	v_or_b32_e32 v88, 6, v86
	v_max_i32_e32 v88, 1, v88
	v_add_u32_e32 v88, -1, v88
	v_min_u32_e32 v88, 0xffff, v88
	v_mul_u32_u24_e32 v208, 0xe00, v88
	s_waitcnt vmcnt(0)
	v_cndmask_b32_e32 v215, 0, v93, vcc
	v_cndmask_b32_e32 v216, 0, v92, vcc
	v_lshl_add_u64 v[92:93], v[56:57], 0, v[208:209]
	v_cndmask_b32_e32 v203, 0, v91, vcc
	v_cndmask_b32_e32 v204, 0, v90, vcc
	v_cndmask_b32_e32 v205, 0, v89, vcc
	v_cndmask_b32_e32 v207, 0, v95, vcc
	v_cndmask_b32_e32 v214, 0, v94, vcc
	global_load_dwordx4 v[88:91], v[92:93], off offset:512
	s_nop 0
	global_load_dwordx4 v[92:95], v[92:93], off offset:1024
	s_waitcnt vmcnt(1)
	v_cndmask_b32_e32 v136, 0, v88, vcc
	v_or_b32_e32 v88, 7, v86
	v_max_i32_e32 v88, 1, v88
	v_add_u32_e32 v88, -1, v88
	v_min_u32_e32 v88, 0xffff, v88
	v_mul_u32_u24_e32 v208, 0xe00, v88
	s_waitcnt vmcnt(0)
	v_cndmask_b32_e32 v137, 0, v93, vcc
	v_cndmask_b32_e32 v139, 0, v92, vcc
	v_lshl_add_u64 v[92:93], v[56:57], 0, v[208:209]
	v_cndmask_b32_e32 v124, 0, v91, vcc
	v_cndmask_b32_e32 v126, 0, v90, vcc
	v_cndmask_b32_e32 v132, 0, v89, vcc
	v_cndmask_b32_e32 v127, 0, v95, vcc
	v_cndmask_b32_e32 v133, 0, v94, vcc
	global_load_dwordx4 v[88:91], v[92:93], off offset:512
	s_nop 0
	global_load_dwordx4 v[92:95], v[92:93], off offset:1024
	s_waitcnt vmcnt(1)
	v_cndmask_b32_e32 v138, 0, v88, vcc
	v_max_i32_e32 v88, -7, v86
	v_add_u32_e32 v88, 7, v88
	v_min_u32_e32 v88, 0xffff, v88
	v_mul_u32_u24_e32 v208, 0xe00, v88
	s_waitcnt vmcnt(0)
	v_cndmask_b32_e32 v130, 0, v93, vcc
	v_cndmask_b32_e32 v134, 0, v92, vcc
	v_lshl_add_u64 v[92:93], v[56:57], 0, v[208:209]
	v_cndmask_b32_e32 v129, 0, v91, vcc
	v_cndmask_b32_e32 v131, 0, v90, vcc
	v_cndmask_b32_e32 v135, 0, v89, vcc
	v_cndmask_b32_e32 v125, 0, v95, vcc
	v_cndmask_b32_e32 v128, 0, v94, vcc
	global_load_dwordx4 v[88:91], v[92:93], off offset:512
	s_nop 0
	global_load_dwordx4 v[92:95], v[92:93], off offset:1024
	v_max_i32_e32 v86, -8, v86
	v_add_u32_e32 v86, 8, v86
	v_min_u32_e32 v86, 0xffff, v86
	v_mul_u32_u24_e32 v208, 0xe00, v86
	s_waitcnt vmcnt(1)
	v_cndmask_b32_e32 v108, 0, v91, vcc
	v_cndmask_b32_e32 v110, 0, v90, vcc
	v_lshl_add_u64 v[90:91], v[56:57], 0, v[208:209]
	v_cndmask_b32_e32 v115, 0, v89, vcc
	v_cndmask_b32_e32 v120, 0, v88, vcc
	s_waitcnt vmcnt(0)
	v_cndmask_b32_e32 v111, 0, v95, vcc
	v_cndmask_b32_e32 v116, 0, v94, vcc
	v_cndmask_b32_e32 v121, 0, v93, vcc
	v_cndmask_b32_e32 v123, 0, v92, vcc
	v_cmp_gt_u32_e32 vcc, s15, v87
	global_load_dwordx4 v[86:89], v[90:91], off offset:512
	s_nop 0
	global_load_dwordx4 v[90:93], v[90:91], off offset:1024
	v_lshlrev_b32_e32 v208, 16, v52
	v_and_b32_e32 v52, 0xffff0000, v52
	s_waitcnt vmcnt(1)
	v_cndmask_b32_e32 v113, 0, v89, vcc
	v_cndmask_b32_e32 v117, 0, v88, vcc
	v_cndmask_b32_e32 v119, 0, v87, vcc
	v_cndmask_b32_e32 v122, 0, v86, vcc
	v_lshlrev_b32_e32 v86, 16, v97
	v_lshlrev_b32_e32 v87, 16, v161
	v_lshlrev_b32_e32 v88, 16, v98
	v_lshlrev_b32_e32 v89, 16, v169
	v_pk_mul_f32 v[100:101], v[86:87], v[88:89]
	v_and_b32_e32 v87, 0xffff0000, v161
	v_and_b32_e32 v86, 0xffff0000, v97
	v_and_b32_e32 v89, 0xffff0000, v169
	v_and_b32_e32 v88, 0xffff0000, v98
	v_pk_mul_f32 v[98:99], v[86:87], v[88:89]
	v_lshlrev_b32_e32 v86, 16, v96
	v_lshlrev_b32_e32 v87, 16, v159
	v_lshlrev_b32_e32 v88, 16, v149
	v_lshlrev_b32_e32 v89, 16, v167
	v_pk_mul_f32 v[94:95], v[86:87], v[88:89]
	v_and_b32_e32 v87, 0xffff0000, v159
	v_and_b32_e32 v86, 0xffff0000, v96
	v_and_b32_e32 v89, 0xffff0000, v167
	v_and_b32_e32 v88, 0xffff0000, v149
	v_pk_mul_f32 v[96:97], v[86:87], v[88:89]
	v_lshlrev_b32_e32 v86, 16, v143
	v_lshlrev_b32_e32 v87, 16, v157
	v_lshlrev_b32_e32 v88, 16, v147
	v_lshlrev_b32_e32 v89, 16, v165
	s_waitcnt vmcnt(0)
	v_cndmask_b32_e32 v114, 0, v91, vcc
	v_cndmask_b32_e32 v118, 0, v90, vcc
	v_pk_mul_f32 v[90:91], v[86:87], v[88:89]
	v_and_b32_e32 v87, 0xffff0000, v157
	v_and_b32_e32 v86, 0xffff0000, v143
	v_and_b32_e32 v89, 0xffff0000, v165
	v_and_b32_e32 v88, 0xffff0000, v147
	v_cndmask_b32_e32 v109, 0, v93, vcc
	v_cndmask_b32_e32 v112, 0, v92, vcc
	v_pk_mul_f32 v[92:93], v[86:87], v[88:89]
	v_lshlrev_b32_e32 v86, 16, v141
	v_lshlrev_b32_e32 v87, 16, v155
	v_lshlrev_b32_e32 v88, 16, v145
	v_lshlrev_b32_e32 v89, 16, v163
	v_pk_mul_f32 v[86:87], v[86:87], v[88:89]
	v_and_b32_e32 v88, 0xffff0000, v141
	v_lshlrev_b32_e32 v143, 16, v190
	v_lshlrev_b32_e32 v141, 16, v194
	v_pk_mul_f32 v[172:173], v[60:61], v[100:101]
	v_pk_mul_f32 v[140:141], v[140:141], v[142:143]
	v_and_b32_e32 v147, 0xffff0000, v190
	v_fma_f32 v142, v8, v140, v172
	v_add_f32_e32 v142, v142, v173
	v_mul_f32_e32 v172, v142, v208
	v_pk_mul_f32 v[142:143], v[60:61], v[140:141]
	v_and_b32_e32 v145, 0xffff0000, v194
	v_fma_f32 v140, v8, v101, v142
	v_pk_mul_f32 v[174:175], v[4:5], v[98:99]
	v_add_f32_e32 v140, v140, v143
	v_pk_mul_f32 v[142:143], v[144:145], v[146:147]
	v_and_b32_e32 v89, 0xffff0000, v155
	v_fma_f32 v144, v9, v142, v174
	v_add_f32_e32 v144, v144, v175
	v_mul_f32_e32 v173, v144, v52
	v_pk_mul_f32 v[144:145], v[4:5], v[142:143]
	v_and_b32_e32 v155, 0xffff0000, v189
	v_lshlrev_b32_e32 v149, 16, v193
	v_fma_f32 v52, v9, v99, v144
	v_pk_mul_f32 v[176:177], v[66:67], v[94:95]
	v_pk_mul_f32 v[178:179], v[6:7], v[96:97]
	v_lshlrev_b32_e32 v159, 16, v188
	v_and_b32_e32 v163, 0xffff0000, v188
	v_lshlrev_b32_e32 v188, 16, v48
	v_and_b32_e32 v48, 0xffff0000, v48
	v_add_f32_e32 v52, v52, v145
	v_pk_mul_f32 v[144:145], v[148:149], v[150:151]
	v_pk_mul_f32 v[148:149], v[152:153], v[154:155]
	v_mul_f32_e32 v142, v52, v48
	v_and_b32_e32 v151, 0xffff0000, v53
	v_lshlrev_b32_e32 v150, 16, v53
	v_mov_b32_e32 v52, v144
	v_mov_b32_e32 v53, v148
	v_mov_b32_e32 v152, v176
	v_mov_b32_e32 v153, v178
	v_pk_fma_f32 v[52:53], v[10:11], v[52:53], v[152:153]
	v_mov_b32_e32 v178, v177
	v_pk_add_f32 v[52:53], v[52:53], v[178:179]
	v_mul_f32_e32 v174, v173, v173
	v_pk_mul_f32 v[52:53], v[52:53], v[150:151]
	v_fmac_f32_e32 v174, v172, v172
	v_pk_mul_f32 v[150:151], v[52:53], v[52:53]
	v_pk_mul_f32 v[146:147], v[66:67], v[144:145]
	v_add_f32_e32 v48, v150, v174
	v_add_f32_e32 v144, v151, v48
	v_pk_mul_f32 v[150:151], v[6:7], v[148:149]
	v_and_b32_e32 v153, 0xffff0000, v49
	v_lshlrev_b32_e32 v152, 16, v49
	v_mov_b32_e32 v48, v95
	v_mov_b32_e32 v49, v97
	v_mov_b32_e32 v154, v146
	v_mov_b32_e32 v155, v150
	v_pk_fma_f32 v[48:49], v[10:11], v[48:49], v[154:155]
	v_mov_b32_e32 v150, v147
	v_lshlrev_b32_e32 v157, 16, v192
	v_and_b32_e32 v161, 0xffff0000, v192
	v_pk_add_f32 v[48:49], v[48:49], v[150:151]
	v_pk_mul_f32 v[180:181], v[72:73], v[90:91]
	v_pk_mul_f32 v[182:183], v[16:17], v[92:93]
	v_pk_mul_f32 v[146:147], v[48:49], v[152:153]
	v_pk_mul_f32 v[150:151], v[156:157], v[158:159]
	v_pk_mul_f32 v[152:153], v[160:161], v[162:163]
	v_mov_b32_e32 v156, v150
	v_mov_b32_e32 v157, v152
	v_mov_b32_e32 v158, v180
	v_mov_b32_e32 v159, v182
	v_pk_fma_f32 v[156:157], v[20:21], v[156:157], v[158:159]
	v_mov_b32_e32 v182, v181
	v_and_b32_e32 v155, 0xffff0000, v54
	v_lshlrev_b32_e32 v154, 16, v54
	v_pk_add_f32 v[156:157], v[156:157], v[182:183]
	v_mul_f32_e32 v140, v140, v188
	v_mul_f32_e32 v175, v142, v142
	v_pk_mul_f32 v[154:155], v[156:157], v[154:155]
	v_fmac_f32_e32 v175, v140, v140
	v_pk_mul_f32 v[48:49], v[146:147], v[146:147]
	v_pk_mul_f32 v[156:157], v[154:155], v[154:155]
	v_add_f32_e32 v48, v48, v175
	v_add_f32_e32 v54, v156, v144
	v_add_f32_e32 v148, v49, v48
	v_pk_mul_f32 v[48:49], v[72:73], v[150:151]
	v_add_f32_e32 v144, v157, v54
	v_pk_mul_f32 v[156:157], v[16:17], v[152:153]
	v_mov_b32_e32 v160, v91
	v_mov_b32_e32 v161, v93
	v_mov_b32_e32 v162, v48
	v_mov_b32_e32 v163, v156
	v_pk_fma_f32 v[160:161], v[20:21], v[160:161], v[162:163]
	v_mov_b32_e32 v156, v49
	v_and_b32_e32 v159, 0xffff0000, v50
	v_lshlrev_b32_e32 v158, 16, v50
	v_pk_add_f32 v[48:49], v[160:161], v[156:157]
	v_pk_mul_f32 v[88:89], v[88:89], v[186:187]
	v_pk_mul_f32 v[156:157], v[48:49], v[158:159]
	v_lshlrev_b32_e32 v167, 16, v171
	v_pk_mul_f32 v[48:49], v[156:157], v[156:157]
	v_and_b32_e32 v171, 0xffff0000, v171
	v_lshlrev_b32_e32 v165, 16, v191
	v_and_b32_e32 v169, 0xffff0000, v191
	v_add_f32_e32 v48, v48, v148
	v_pk_mul_f32 v[184:185], v[78:79], v[86:87]
	v_pk_mul_f32 v[186:187], v[18:19], v[88:89]
	v_add_f32_e32 v148, v49, v48
	v_pk_mul_f32 v[158:159], v[164:165], v[166:167]
	v_pk_mul_f32 v[48:49], v[168:169], v[170:171]
	v_and_b32_e32 v163, 0xffff0000, v55
	v_lshlrev_b32_e32 v162, 16, v55
	v_mov_b32_e32 v54, v158
	v_mov_b32_e32 v55, v48
	v_mov_b32_e32 v164, v184
	v_mov_b32_e32 v165, v186
	v_pk_fma_f32 v[54:55], v[22:23], v[54:55], v[164:165]
	v_mov_b32_e32 v186, v185
	v_pk_add_f32 v[54:55], v[54:55], v[186:187]
	v_pk_mul_f32 v[160:161], v[78:79], v[158:159]
	v_pk_mul_f32 v[54:55], v[54:55], v[162:163]
	v_lshlrev_b32_e32 v164, 16, v200
	v_pk_mul_f32 v[162:163], v[54:55], v[54:55]
	v_lshlrev_b32_e32 v166, 16, v196
	v_add_f32_e32 v50, v162, v144
	v_add_f32_e32 v50, v163, v50
	v_and_b32_e32 v162, 0xffff0000, v197
	v_and_b32_e32 v163, 0xffff0000, v205
	v_lshlrev_b32_e32 v167, 16, v204
	v_lshlrev_b32_e32 v165, 16, v214
	s_waitcnt lgkmcnt(0)
	s_nop 1
	v_add_f32_dpp v50, v50, v50 quad_perm:[1,0,3,2] row_mask:0xf bank_mask:0xf
	v_and_b32_e32 v168, 0xffff0000, v200
	v_and_b32_e32 v170, 0xffff0000, v196
	v_and_b32_e32 v171, 0xffff0000, v204
	v_and_b32_e32 v169, 0xffff0000, v214
	s_waitcnt lgkmcnt(0)
	s_nop 1
	v_add_f32_dpp v50, v50, v50 quad_perm:[2,3,0,1] row_mask:0xf bank_mask:0xf
	v_lshlrev_b32_e32 v174, 16, v195
	v_lshlrev_b32_e32 v175, 16, v203
	v_and_b32_e32 v176, 0xffff0000, v199
	v_and_b32_e32 v178, 0xffff0000, v195
	s_waitcnt lgkmcnt(0)
	s_nop 1
	v_add_f32_dpp v50, v50, v50 row_half_mirror row_mask:0xf bank_mask:0xf
	v_and_b32_e32 v179, 0xffff0000, v203
	v_and_b32_e32 v177, 0xffff0000, v207
	s_waitcnt lgkmcnt(0)
	s_nop 1
	v_add_f32_dpp v50, v50, v50 row_mirror row_mask:0xf bank_mask:0xf
	s_nop 1
	v_mov_b32_e32 v144, v50
	s_nop 1
	v_permlane16_swap_b32_e32 v144, v50
	s_waitcnt lgkmcnt(0)
	v_add_f32_e32 v50, v50, v144
	v_fmamk_f32 v50, v50, 0x3b800000, v244
	v_cmp_gt_f32_e32 vcc, s7, v50
	v_mul_f32_e32 v144, 0x4b800000, v50
	s_nop 0
	v_cndmask_b32_e32 v50, v50, v144, vcc
	v_rsq_f32_e32 v50, v50
	s_nop 0
	v_mul_f32_e32 v144, 0x45800000, v50
	v_cndmask_b32_e32 v50, v50, v144, vcc
	v_mul_f32_e32 v53, v53, v50
	v_mul_f32_e32 v144, v172, v50
	v_mul_f32_e32 v150, v173, v50
	v_mul_f32_e32 v152, v52, v50
	v_cvt_pk_bf16_f32 v52, v144, v150
	v_cvt_pk_bf16_f32 v53, v152, v53
	v_mul_f32_e32 v154, v154, v50
	v_mul_f32_e32 v155, v155, v50
	v_mul_f32_e32 v158, v54, v50
	v_mul_f32_e32 v50, v55, v50
	v_cvt_pk_bf16_f32 v54, v154, v155
	v_cvt_pk_bf16_f32 v55, v158, v50
	global_store_dwordx4 v[84:85], v[52:55], off
	v_mov_b32_e32 v50, v87
	v_mov_b32_e32 v154, v160
	v_pk_mul_f32 v[52:53], v[18:19], v[48:49]
	v_and_b32_e32 v55, 0xffff0000, v51
	v_lshlrev_b32_e32 v54, 16, v51
	v_mov_b32_e32 v51, v89
	v_mov_b32_e32 v155, v52
	v_pk_fma_f32 v[50:51], v[22:23], v[50:51], v[154:155]
	v_mov_b32_e32 v52, v161
	v_pk_add_f32 v[50:51], v[50:51], v[52:53]
	v_lshlrev_b32_e32 v154, 16, v201
	v_pk_mul_f32 v[50:51], v[50:51], v[54:55]
	v_lshlrev_b32_e32 v155, 16, v215
	v_pk_mul_f32 v[52:53], v[50:51], v[50:51]
	v_and_b32_e32 v160, 0xffff0000, v201
	v_add_f32_e32 v48, v52, v148
	v_add_f32_e32 v48, v53, v48
	v_and_b32_e32 v161, 0xffff0000, v215
	v_mov_b32_e32 v148, v145
	v_mov_b32_e32 v152, v151
	v_lshlrev_b32_e32 v172, 16, v199
	s_waitcnt lgkmcnt(0)
	s_nop 1
	v_add_f32_dpp v48, v48, v48 quad_perm:[1,0,3,2] row_mask:0xf bank_mask:0xf
	v_lshlrev_b32_e32 v173, 16, v207
	s_waitcnt lgkmcnt(0)
	s_nop 1
	v_add_f32_dpp v48, v48, v48 quad_perm:[2,3,0,1] row_mask:0xf bank_mask:0xf
	s_waitcnt lgkmcnt(0)
	s_nop 1
	v_add_f32_dpp v48, v48, v48 row_half_mirror row_mask:0xf bank_mask:0xf
	s_waitcnt lgkmcnt(0)
	s_nop 1
	v_add_f32_dpp v48, v48, v48 row_mirror row_mask:0xf bank_mask:0xf
	s_nop 1
	v_mov_b32_e32 v52, v48
	s_nop 1
	v_permlane16_swap_b32_e32 v52, v48
	s_waitcnt lgkmcnt(0)
	v_add_f32_e32 v48, v48, v52
	v_fmamk_f32 v48, v48, 0x3b800000, v244
	v_cmp_gt_f32_e32 vcc, s7, v48
	v_mul_f32_e32 v52, 0x4b800000, v48
	s_nop 0
	v_cndmask_b32_e32 v48, v48, v52, vcc
	v_rsq_f32_e32 v48, v48
	s_nop 0
	v_mul_f32_e32 v52, 0x45800000, v48
	v_cndmask_b32_e32 v48, v48, v52, vcc
	v_mul_f32_e32 v52, v140, v48
	v_mul_f32_e32 v53, v142, v48
	v_mul_f32_e32 v54, v146, v48
	v_mul_f32_e32 v55, v147, v48
	v_mul_f32_e32 v140, v156, v48
	v_mul_f32_e32 v142, v157, v48
	v_mul_f32_e32 v144, v50, v48
	v_mul_f32_e32 v48, v51, v48
	v_cvt_pk_bf16_f32 v50, v52, v53
	v_cvt_pk_bf16_f32 v51, v54, v55
	v_cvt_pk_bf16_f32 v52, v140, v142
	v_cvt_pk_bf16_f32 v53, v144, v48
	global_store_dwordx4 v[84:85], v[50:53], off offset:2048
	v_lshlrev_b32_e32 v48, 16, v44
	v_and_b32_e32 v54, 0xffff0000, v202
	v_lshlrev_b32_e32 v50, 16, v202
	v_lshlrev_b32_e32 v52, 16, v198
	v_lshlrev_b32_e32 v53, 16, v206
	v_lshlrev_b32_e32 v51, 16, v216
	v_pk_mul_f32 v[180:181], v[50:51], v[52:53]
	v_and_b32_e32 v146, 0xffff0000, v198
	v_pk_mov_b32 v[50:51], v[100:101], v[180:181] op_sel:[1,0]
	v_and_b32_e32 v147, 0xffff0000, v206
	v_pk_mul_f32 v[50:51], v[60:61], v[50:51]
	v_and_b32_e32 v55, 0xffff0000, v216
	v_fma_f32 v50, v8, v141, v50
	v_add_f32_e32 v50, v50, v51
	v_mul_f32_e32 v144, v50, v48
	v_pk_mul_f32 v[50:51], v[62:63], v[180:181]
	v_pk_mul_f32 v[54:55], v[54:55], v[146:147]
	v_fma_f32 v48, v0, v141, v50
	v_add_f32_e32 v48, v48, v51
	v_pk_mov_b32 v[50:51], v[98:99], v[54:55] op_sel:[1,0]
	v_lshlrev_b32_e32 v140, 16, v40
	v_pk_mul_f32 v[50:51], v[4:5], v[50:51]
	v_mul_f32_e32 v150, v48, v140
	v_fma_f32 v48, v9, v143, v50
	v_lshlrev_b32_e32 v156, 16, v197
	v_and_b32_e32 v44, 0xffff0000, v44
	v_lshlrev_b32_e32 v157, 16, v205
	v_add_f32_e32 v48, v48, v51
	v_pk_mul_f32 v[50:51], v[64:65], v[54:55]
	v_mul_f32_e32 v146, v48, v44
	v_fma_f32 v44, v1, v143, v50
	v_pk_mul_f32 v[98:99], v[154:155], v[156:157]
	v_add_f32_e32 v44, v44, v51
	v_pk_mov_b32 v[50:51], v[94:95], v[98:99] op_sel:[1,0]
	v_pk_mul_f32 v[94:95], v[160:161], v[162:163]
	v_and_b32_e32 v40, 0xffff0000, v40
	v_pk_mov_b32 v[96:97], v[96:97], v[94:95] op_sel:[1,0]
	v_pk_mul_f32 v[50:51], v[66:67], v[50:51]
	v_pk_mul_f32 v[96:97], v[6:7], v[96:97]
	v_mul_f32_e32 v147, v44, v40
	v_and_b32_e32 v101, 0xffff0000, v45
	v_lshlrev_b32_e32 v100, 16, v45
	v_mov_b32_e32 v44, v50
	v_mov_b32_e32 v45, v96
	v_pk_fma_f32 v[44:45], v[10:11], v[148:149], v[44:45]
	v_mov_b32_e32 v96, v51
	v_pk_add_f32 v[44:45], v[44:45], v[96:97]
	v_mul_f32_e32 v48, v146, v146
	v_pk_mul_f32 v[44:45], v[44:45], v[100:101]
	v_fmac_f32_e32 v48, v144, v144
	v_pk_mul_f32 v[50:51], v[44:45], v[44:45]
	v_pk_mul_f32 v[52:53], v[68:69], v[98:99]
	v_add_f32_e32 v40, v50, v48
	v_add_f32_e32 v48, v51, v40
	v_pk_mul_f32 v[50:51], v[70:71], v[94:95]
	v_and_b32_e32 v97, 0xffff0000, v41
	v_lshlrev_b32_e32 v96, 16, v41
	v_mov_b32_e32 v40, v52
	v_mov_b32_e32 v41, v50
	v_pk_fma_f32 v[40:41], v[2:3], v[148:149], v[40:41]
	v_mov_b32_e32 v50, v53
	v_pk_add_f32 v[40:41], v[40:41], v[50:51]
	v_mul_f32_e32 v140, v147, v147
	v_pk_mul_f32 v[96:97], v[40:41], v[96:97]
	v_fmac_f32_e32 v140, v150, v150
	v_pk_mul_f32 v[40:41], v[96:97], v[96:97]
	v_pk_mul_f32 v[100:101], v[164:165], v[166:167]
	v_add_f32_e32 v40, v40, v140
	v_add_f32_e32 v142, v41, v40
	v_pk_mov_b32 v[40:41], v[90:91], v[100:101] op_sel:[1,0]
	v_pk_mul_f32 v[90:91], v[168:169], v[170:171]
	v_pk_mul_f32 v[40:41], v[72:73], v[40:41]
	v_pk_mov_b32 v[52:53], v[92:93], v[90:91] op_sel:[1,0]
	v_mov_b32_e32 v140, v40
	v_pk_mul_f32 v[52:53], v[16:17], v[52:53]
	v_and_b32_e32 v93, 0xffff0000, v46
	v_mov_b32_e32 v141, v52
	v_pk_fma_f32 v[140:141], v[20:21], v[152:153], v[140:141]
	v_mov_b32_e32 v52, v41
	v_lshlrev_b32_e32 v92, 16, v46
	v_pk_add_f32 v[40:41], v[140:141], v[52:53]
	v_pk_mul_f32 v[50:51], v[74:75], v[100:101]
	v_pk_mul_f32 v[52:53], v[40:41], v[92:93]
	v_mov_b32_e32 v140, v50
	v_pk_mul_f32 v[40:41], v[52:53], v[52:53]
	v_and_b32_e32 v93, 0xffff0000, v42
	v_add_f32_e32 v40, v40, v48
	v_add_f32_e32 v145, v41, v40
	v_pk_mul_f32 v[40:41], v[76:77], v[90:91]
	v_lshlrev_b32_e32 v92, 16, v42
	v_mov_b32_e32 v141, v40
	v_pk_fma_f32 v[140:141], v[12:13], v[152:153], v[140:141]
	v_mov_b32_e32 v40, v51
	v_pk_add_f32 v[40:41], v[140:141], v[40:41]
	v_pk_mul_f32 v[140:141], v[172:173], v[174:175]
	v_pk_mul_f32 v[92:93], v[40:41], v[92:93]
	v_and_b32_e32 v143, 0xffff0000, v47
	v_pk_mul_f32 v[40:41], v[92:93], v[92:93]
	v_mov_b32_e32 v48, v159
	v_add_f32_e32 v40, v40, v142
	v_add_f32_e32 v148, v41, v40
	v_pk_mov_b32 v[40:41], v[86:87], v[140:141] op_sel:[1,0]
	v_lshlrev_b32_e32 v142, 16, v47
	v_pk_mul_f32 v[50:51], v[78:79], v[40:41]
	v_pk_mul_f32 v[40:41], v[176:177], v[178:179]
	v_mov_b32_e32 v46, v50
	v_pk_mov_b32 v[88:89], v[88:89], v[40:41] op_sel:[1,0]
	v_pk_mul_f32 v[86:87], v[80:81], v[140:141]
	v_pk_mul_f32 v[88:89], v[18:19], v[88:89]
	v_and_b32_e32 v149, 0xffff0000, v129
	v_mov_b32_e32 v47, v88
	v_pk_fma_f32 v[46:47], v[22:23], v[48:49], v[46:47]
	v_mov_b32_e32 v88, v51
	v_pk_add_f32 v[46:47], v[46:47], v[88:89]
	s_nop 0
	v_pk_mul_f32 v[46:47], v[46:47], v[142:143]
	v_lshlrev_b32_e32 v143, 16, v125
	v_pk_mul_f32 v[50:51], v[46:47], v[46:47]
	v_lshlrev_b32_e32 v142, 16, v127
	v_add_f32_e32 v42, v50, v145
	v_add_f32_e32 v42, v51, v42
	v_lshlrev_b32_e32 v145, 16, v129
	s_waitcnt lgkmcnt(0)
	s_nop 1
	v_add_f32_dpp v42, v42, v42 quad_perm:[1,0,3,2] row_mask:0xf bank_mask:0xf
	s_waitcnt lgkmcnt(0)
	s_nop 1
	v_add_f32_dpp v42, v42, v42 quad_perm:[2,3,0,1] row_mask:0xf bank_mask:0xf
	s_waitcnt lgkmcnt(0)
	s_nop 1
	v_add_f32_dpp v42, v42, v42 row_half_mirror row_mask:0xf bank_mask:0xf
	s_waitcnt lgkmcnt(0)
	s_nop 1
	v_add_f32_dpp v42, v42, v42 row_mirror row_mask:0xf bank_mask:0xf
	s_nop 1
	v_mov_b32_e32 v50, v42
	s_nop 1
	v_permlane16_swap_b32_e32 v50, v42
	s_waitcnt lgkmcnt(0)
	v_add_f32_e32 v42, v42, v50
	v_fmamk_f32 v42, v42, 0x3b800000, v244
	v_cmp_gt_f32_e32 vcc, s7, v42
	v_mul_f32_e32 v50, 0x4b800000, v42
	s_nop 0
	v_cndmask_b32_e32 v42, v42, v50, vcc
	v_rsq_f32_e32 v42, v42
	s_nop 0
	v_mul_f32_e32 v50, 0x45800000, v42
	v_cndmask_b32_e32 v42, v42, v50, vcc
	v_add_co_u32_e32 v88, vcc, s34, v84
	v_mul_f32_e32 v50, v144, v42
	v_mul_f32_e32 v51, v146, v42
	v_mul_f32_e32 v44, v44, v42
	v_addc_co_u32_e32 v89, vcc, 0, v85, vcc
	v_mul_f32_e32 v45, v45, v42
	v_mul_f32_e32 v52, v52, v42
	v_mul_f32_e32 v53, v53, v42
	v_mul_f32_e32 v46, v46, v42
	v_cvt_pk_bf16_f32 v50, v50, v51
	v_cvt_pk_bf16_f32 v51, v44, v45
	v_add_co_u32_e32 v44, vcc, s15, v84
	v_mul_f32_e32 v42, v47, v42
	v_cvt_pk_bf16_f32 v52, v52, v53
	v_cvt_pk_bf16_f32 v53, v46, v42
	s_nop 0
	v_addc_co_u32_e32 v45, vcc, 0, v85, vcc
	v_pk_mul_f32 v[46:47], v[82:83], v[40:41]
	global_store_dwordx4 v[44:45], v[50:53], off offset:-4096
	v_mov_b32_e32 v42, v86
	v_lshlrev_b32_e32 v144, 16, v124
	v_and_b32_e32 v51, 0xffff0000, v43
	v_lshlrev_b32_e32 v50, 16, v43
	v_mov_b32_e32 v43, v46
	v_pk_fma_f32 v[42:43], v[14:15], v[48:49], v[42:43]
	v_mov_b32_e32 v46, v87
	v_pk_add_f32 v[42:43], v[42:43], v[46:47]
	v_lshlrev_b32_e32 v86, 16, v132
	v_pk_mul_f32 v[42:43], v[42:43], v[50:51]
	v_lshlrev_b32_e32 v87, 16, v135
	v_pk_mul_f32 v[46:47], v[42:43], v[42:43]
	v_lshlrev_b32_e32 v53, 16, v130
	v_add_f32_e32 v46, v46, v148
	v_add_f32_e32 v46, v47, v46
	v_and_b32_e32 v148, 0xffff0000, v124
	v_lshlrev_b32_e32 v124, 16, v36
	v_and_b32_e32 v36, 0xffff0000, v36
	v_and_b32_e32 v146, 0xffff0000, v127
	s_waitcnt lgkmcnt(0)
	s_nop 1
	v_add_f32_dpp v46, v46, v46 quad_perm:[1,0,3,2] row_mask:0xf bank_mask:0xf
	v_and_b32_e32 v127, 0xffff0000, v131
	s_waitcnt lgkmcnt(0)
	s_nop 1
	v_add_f32_dpp v46, v46, v46 quad_perm:[2,3,0,1] row_mask:0xf bank_mask:0xf
	s_waitcnt lgkmcnt(0)
	s_nop 1
	v_add_f32_dpp v46, v46, v46 row_half_mirror row_mask:0xf bank_mask:0xf
	s_waitcnt lgkmcnt(0)
	s_nop 1
	v_add_f32_dpp v46, v46, v46 row_mirror row_mask:0xf bank_mask:0xf
	s_nop 1
	v_mov_b32_e32 v47, v46
	s_nop 1
	v_permlane16_swap_b32_e32 v47, v46
	s_waitcnt lgkmcnt(0)
	v_add_f32_e32 v46, v46, v47
	v_fmamk_f32 v46, v46, 0x3b800000, v244
	v_cmp_gt_f32_e32 vcc, s7, v46
	v_mul_f32_e32 v47, 0x4b800000, v46
	s_nop 0
	v_cndmask_b32_e32 v46, v46, v47, vcc
	v_rsq_f32_e32 v46, v46
	s_nop 0
	v_mul_f32_e32 v47, 0x45800000, v46
	v_cndmask_b32_e32 v46, v46, v47, vcc
	v_mul_f32_e32 v47, v150, v46
	v_mul_f32_e32 v48, v147, v46
	v_mul_f32_e32 v49, v96, v46
	v_mul_f32_e32 v50, v97, v46
	v_mul_f32_e32 v51, v92, v46
	v_mul_f32_e32 v52, v93, v46
	v_mul_f32_e32 v42, v42, v46
	v_mul_f32_e32 v43, v43, v46
	v_cvt_pk_bf16_f32 v46, v47, v48
	v_cvt_pk_bf16_f32 v47, v49, v50
	v_cvt_pk_bf16_f32 v48, v51, v52
	v_cvt_pk_bf16_f32 v49, v42, v43
	global_store_dwordx4 v[88:89], v[46:49], off offset:2048
	v_lshlrev_b32_e32 v42, 16, v139
	v_lshlrev_b32_e32 v43, 16, v134
	v_lshlrev_b32_e32 v46, 16, v136
	v_lshlrev_b32_e32 v47, 16, v138
	v_pk_mul_f32 v[42:43], v[42:43], v[46:47]
	v_mov_b32_e32 v46, v180
	v_mov_b32_e32 v47, v42
	v_pk_mul_f32 v[46:47], v[60:61], v[46:47]
	v_and_b32_e32 v48, 0xffff0000, v139
	v_fma_f32 v46, v8, v181, v46
	v_add_f32_e32 v46, v46, v47
	v_mul_f32_e32 v124, v46, v124
	v_pk_mul_f32 v[46:47], v[62:63], v[42:43]
	v_and_b32_e32 v50, 0xffff0000, v136
	v_fma_f32 v46, v0, v181, v46
	v_and_b32_e32 v51, 0xffff0000, v138
	v_and_b32_e32 v49, 0xffff0000, v134
	v_and_b32_e32 v147, 0xffff0000, v125
	v_lshlrev_b32_e32 v125, 16, v32
	v_add_f32_e32 v46, v46, v47
	v_mul_f32_e32 v125, v46, v125
	v_pk_mul_f32 v[46:47], v[48:49], v[50:51]
	v_mov_b32_e32 v48, v54
	v_mov_b32_e32 v49, v46
	v_pk_mul_f32 v[48:49], v[4:5], v[48:49]
	v_lshlrev_b32_e32 v52, 16, v137
	v_fma_f32 v48, v9, v55, v48
	v_add_f32_e32 v48, v48, v49
	v_and_b32_e32 v88, 0xffff0000, v137
	v_lshlrev_b32_e32 v97, 16, v128
	v_and_b32_e32 v137, 0xffff0000, v128
	v_mul_f32_e32 v128, v48, v36
	v_pk_mul_f32 v[48:49], v[64:65], v[46:47]
	v_and_b32_e32 v92, 0xffff0000, v132
	v_and_b32_e32 v93, 0xffff0000, v135
	v_and_b32_e32 v89, 0xffff0000, v130
	v_fma_f32 v36, v1, v55, v48
	v_add_f32_e32 v36, v36, v49
	v_pk_mul_f32 v[48:49], v[52:53], v[86:87]
	v_pk_mul_f32 v[54:55], v[88:89], v[92:93]
	v_mov_b32_e32 v50, v98
	v_mov_b32_e32 v51, v48
	v_mov_b32_e32 v86, v94
	v_mov_b32_e32 v87, v54
	v_and_b32_e32 v32, 0xffff0000, v32
	v_pk_mul_f32 v[50:51], v[66:67], v[50:51]
	v_pk_mul_f32 v[86:87], v[6:7], v[86:87]
	v_mul_f32_e32 v130, v36, v32
	v_and_b32_e32 v89, 0xffff0000, v37
	v_lshlrev_b32_e32 v88, 16, v37
	v_mov_b32_e32 v94, v99
	v_mov_b32_e32 v36, v50
	v_mov_b32_e32 v37, v86
	v_pk_fma_f32 v[36:37], v[10:11], v[94:95], v[36:37]
	v_mov_b32_e32 v86, v51
	v_pk_add_f32 v[36:37], v[36:37], v[86:87]
	v_mul_f32_e32 v129, v128, v128
	v_pk_mul_f32 v[36:37], v[36:37], v[88:89]
	v_fmac_f32_e32 v129, v124, v124
	v_pk_mul_f32 v[50:51], v[36:37], v[36:37]
	v_pk_mul_f32 v[52:53], v[68:69], v[48:49]
	v_add_f32_e32 v32, v50, v129
	v_add_f32_e32 v98, v51, v32
	v_pk_mul_f32 v[50:51], v[70:71], v[54:55]
	v_and_b32_e32 v87, 0xffff0000, v33
	v_lshlrev_b32_e32 v86, 16, v33
	v_mov_b32_e32 v32, v52
	v_mov_b32_e32 v33, v50
	v_pk_fma_f32 v[32:33], v[2:3], v[94:95], v[32:33]
	v_mov_b32_e32 v50, v53
	v_pk_add_f32 v[32:33], v[32:33], v[50:51]
	v_lshlrev_b32_e32 v96, 16, v133
	v_and_b32_e32 v136, 0xffff0000, v133
	v_lshlrev_b32_e32 v133, 16, v131
	v_mul_f32_e32 v131, v130, v130
	v_pk_mul_f32 v[50:51], v[32:33], v[86:87]
	v_lshlrev_b32_e32 v132, 16, v126
	v_and_b32_e32 v126, 0xffff0000, v126
	v_fmac_f32_e32 v131, v125, v125
	v_pk_mul_f32 v[32:33], v[50:51], v[50:51]
	v_pk_mul_f32 v[52:53], v[96:97], v[132:133]
	v_add_f32_e32 v32, v32, v131
	v_pk_mul_f32 v[88:89], v[136:137], v[126:127]
	v_add_f32_e32 v99, v33, v32
	v_mov_b32_e32 v32, v100
	v_mov_b32_e32 v33, v52
	v_mov_b32_e32 v92, v90
	v_mov_b32_e32 v93, v88
	v_pk_mul_f32 v[32:33], v[72:73], v[32:33]
	v_pk_mul_f32 v[92:93], v[16:17], v[92:93]
	v_mov_b32_e32 v90, v101
	v_mov_b32_e32 v96, v32
	v_mov_b32_e32 v97, v92
	v_pk_fma_f32 v[96:97], v[20:21], v[90:91], v[96:97]
	v_mov_b32_e32 v92, v33
	v_and_b32_e32 v95, 0xffff0000, v38
	v_lshlrev_b32_e32 v94, 16, v38
	v_pk_add_f32 v[32:33], v[96:97], v[92:93]
	v_pk_mul_f32 v[86:87], v[74:75], v[52:53]
	v_pk_mul_f32 v[92:93], v[32:33], v[94:95]
	v_mov_b32_e32 v96, v86
	v_pk_mul_f32 v[32:33], v[92:93], v[92:93]
	v_and_b32_e32 v95, 0xffff0000, v34
	v_add_f32_e32 v32, v32, v98
	v_add_f32_e32 v126, v33, v32
	v_pk_mul_f32 v[32:33], v[76:77], v[88:89]
	v_lshlrev_b32_e32 v94, 16, v34
	v_mov_b32_e32 v97, v32
	v_pk_fma_f32 v[90:91], v[12:13], v[90:91], v[96:97]
	v_mov_b32_e32 v32, v87
	v_pk_add_f32 v[32:33], v[90:91], v[32:33]
	v_pk_mul_f32 v[90:91], v[142:143], v[144:145]
	v_pk_mul_f32 v[86:87], v[32:33], v[94:95]
	v_mov_b32_e32 v98, v40
	v_pk_mul_f32 v[32:33], v[86:87], v[86:87]
	v_and_b32_e32 v101, 0xffff0000, v39
	v_add_f32_e32 v32, v32, v99
	v_add_f32_e32 v127, v33, v32
	v_mov_b32_e32 v32, v140
	v_mov_b32_e32 v33, v90
	v_pk_mul_f32 v[94:95], v[78:79], v[32:33]
	v_pk_mul_f32 v[32:33], v[146:147], v[148:149]
	v_lshlrev_b32_e32 v100, 16, v39
	v_mov_b32_e32 v99, v32
	v_pk_mul_f32 v[98:99], v[18:19], v[98:99]
	v_mov_b32_e32 v40, v141
	v_mov_b32_e32 v38, v94
	v_mov_b32_e32 v39, v98
	v_pk_fma_f32 v[38:39], v[22:23], v[40:41], v[38:39]
	v_mov_b32_e32 v98, v95
	v_pk_add_f32 v[38:39], v[38:39], v[98:99]
	v_pk_mul_f32 v[96:97], v[80:81], v[90:91]
	v_pk_mul_f32 v[38:39], v[38:39], v[100:101]
	v_and_b32_e32 v100, 0xffff0000, v110
	v_pk_mul_f32 v[94:95], v[38:39], v[38:39]
	v_and_b32_e32 v101, 0xffff0000, v117
	v_add_f32_e32 v34, v94, v126
	v_add_f32_e32 v34, v95, v34
	s_waitcnt lgkmcnt(0)
	s_nop 1
	v_add_f32_dpp v34, v34, v34 quad_perm:[1,0,3,2] row_mask:0xf bank_mask:0xf
	s_waitcnt lgkmcnt(0)
	s_nop 1
	v_add_f32_dpp v34, v34, v34 quad_perm:[2,3,0,1] row_mask:0xf bank_mask:0xf
	s_waitcnt lgkmcnt(0)
	s_nop 1
	v_add_f32_dpp v34, v34, v34 row_half_mirror row_mask:0xf bank_mask:0xf
	s_waitcnt lgkmcnt(0)
	s_nop 1
	v_add_f32_dpp v34, v34, v34 row_mirror row_mask:0xf bank_mask:0xf
	s_nop 1
	v_mov_b32_e32 v94, v34
	s_nop 1
	v_permlane16_swap_b32_e32 v94, v34
	s_waitcnt lgkmcnt(0)
	v_add_f32_e32 v34, v34, v94
	v_fmamk_f32 v34, v34, 0x3b800000, v244
	v_cmp_gt_f32_e32 vcc, s7, v34
	v_mul_f32_e32 v94, 0x4b800000, v34
	s_nop 0
	v_cndmask_b32_e32 v34, v34, v94, vcc
	v_rsq_f32_e32 v34, v34
	s_nop 0
	v_mul_f32_e32 v94, 0x45800000, v34
	v_cndmask_b32_e32 v34, v34, v94, vcc
	v_mul_f32_e32 v37, v37, v34
	v_mul_f32_e32 v94, v124, v34
	v_mul_f32_e32 v95, v128, v34
	v_mul_f32_e32 v98, v36, v34
	v_cvt_pk_bf16_f32 v36, v94, v95
	v_cvt_pk_bf16_f32 v37, v98, v37
	v_mul_f32_e32 v92, v92, v34
	v_mul_f32_e32 v93, v93, v34
	v_mul_f32_e32 v99, v38, v34
	v_mul_f32_e32 v34, v39, v34
	v_cvt_pk_bf16_f32 v38, v92, v93
	v_cvt_pk_bf16_f32 v39, v99, v34
	global_store_dwordx4 v[44:45], v[36:39], off
	v_mov_b32_e32 v34, v96
	v_lshlrev_b32_e32 v96, 16, v110
	v_pk_mul_f32 v[36:37], v[82:83], v[32:33]
	v_and_b32_e32 v39, 0xffff0000, v35
	v_lshlrev_b32_e32 v38, 16, v35
	v_mov_b32_e32 v35, v36
	v_pk_fma_f32 v[34:35], v[14:15], v[40:41], v[34:35]
	v_mov_b32_e32 v36, v97
	v_pk_add_f32 v[34:35], v[34:35], v[36:37]
	v_lshlrev_b32_e32 v110, 16, v111
	v_pk_mul_f32 v[34:35], v[34:35], v[38:39]
	v_lshlrev_b32_e32 v94, 16, v116
	v_pk_mul_f32 v[36:37], v[34:35], v[34:35]
	v_and_b32_e32 v98, 0xffff0000, v116
	v_add_f32_e32 v36, v36, v127
	v_add_f32_e32 v36, v37, v36
	v_lshlrev_b32_e32 v116, 16, v108
	v_and_b32_e32 v124, 0xffff0000, v108
	v_lshlrev_b32_e32 v108, 16, v28
	v_and_b32_e32 v28, 0xffff0000, v28
	s_waitcnt lgkmcnt(0)
	s_nop 1
	v_add_f32_dpp v36, v36, v36 quad_perm:[1,0,3,2] row_mask:0xf bank_mask:0xf
	v_and_b32_e32 v92, 0xffff0000, v115
	v_and_b32_e32 v93, 0xffff0000, v119
	v_lshlrev_b32_e32 v95, 16, v112
	v_and_b32_e32 v99, 0xffff0000, v112
	s_waitcnt lgkmcnt(0)
	s_nop 1
	v_add_f32_dpp v36, v36, v36 quad_perm:[2,3,0,1] row_mask:0xf bank_mask:0xf
	v_lshlrev_b32_e32 v97, 16, v117
	v_lshlrev_b32_e32 v117, 16, v113
	s_waitcnt lgkmcnt(0)
	s_nop 1
	v_add_f32_dpp v36, v36, v36 row_half_mirror row_mask:0xf bank_mask:0xf
	s_waitcnt lgkmcnt(0)
	s_nop 1
	v_add_f32_dpp v36, v36, v36 row_mirror row_mask:0xf bank_mask:0xf
	s_nop 1
	v_mov_b32_e32 v37, v36
	s_nop 1
	v_permlane16_swap_b32_e32 v37, v36
	s_waitcnt lgkmcnt(0)
	v_add_f32_e32 v36, v36, v37
	v_fmamk_f32 v36, v36, 0x3b800000, v244
	v_cmp_gt_f32_e32 vcc, s7, v36
	v_mul_f32_e32 v37, 0x4b800000, v36
	s_nop 0
	v_cndmask_b32_e32 v36, v36, v37, vcc
	v_rsq_f32_e32 v36, v36
	s_nop 0
	v_mul_f32_e32 v37, 0x45800000, v36
	v_cndmask_b32_e32 v36, v36, v37, vcc
	v_mul_f32_e32 v37, v125, v36
	v_mul_f32_e32 v38, v130, v36
	v_mul_f32_e32 v39, v50, v36
	v_mul_f32_e32 v40, v51, v36
	v_mul_f32_e32 v41, v86, v36
	v_mul_f32_e32 v50, v87, v36
	v_mul_f32_e32 v51, v34, v36
	v_mul_f32_e32 v86, v35, v36
	v_cvt_pk_bf16_f32 v34, v37, v38
	v_cvt_pk_bf16_f32 v35, v39, v40
	v_cvt_pk_bf16_f32 v36, v41, v50
	v_cvt_pk_bf16_f32 v37, v51, v86
	global_store_dwordx4 v[44:45], v[34:37], off offset:2048
	v_and_b32_e32 v38, 0xffff0000, v123
	v_and_b32_e32 v40, 0xffff0000, v120
	v_lshlrev_b32_e32 v34, 16, v123
	v_lshlrev_b32_e32 v36, 16, v120
	v_lshlrev_b32_e32 v37, 16, v122
	v_lshlrev_b32_e32 v35, 16, v118
	v_pk_mul_f32 v[34:35], v[34:35], v[36:37]
	v_mov_b32_e32 v36, v42
	v_mov_b32_e32 v37, v34
	v_pk_mul_f32 v[34:35], v[62:63], v[34:35]
	v_pk_mul_f32 v[36:37], v[60:61], v[36:37]
	v_fma_f32 v34, v0, v43, v34
	v_lshlrev_b32_e32 v44, 16, v121
	v_and_b32_e32 v86, 0xffff0000, v121
	v_and_b32_e32 v120, 0xffff0000, v111
	v_and_b32_e32 v41, 0xffff0000, v122
	v_and_b32_e32 v39, 0xffff0000, v118
	v_lshlrev_b32_e32 v111, 16, v109
	v_and_b32_e32 v121, 0xffff0000, v109
	v_lshlrev_b32_e32 v109, 16, v24
	v_fma_f32 v36, v8, v43, v36
	v_add_f32_e32 v34, v34, v35
	v_add_f32_e32 v36, v36, v37
	v_mul_f32_e32 v109, v34, v109
	v_pk_mul_f32 v[34:35], v[38:39], v[40:41]
	v_mul_f32_e32 v108, v36, v108
	v_mov_b32_e32 v36, v46
	v_mov_b32_e32 v37, v34
	v_pk_mul_f32 v[36:37], v[4:5], v[36:37]
	v_pk_mul_f32 v[34:35], v[64:65], v[34:35]
	v_fma_f32 v36, v9, v47, v36
	v_add_f32_e32 v36, v36, v37
	v_lshlrev_b32_e32 v50, 16, v115
	v_lshlrev_b32_e32 v51, 16, v119
	v_lshlrev_b32_e32 v45, 16, v114
	v_and_b32_e32 v87, 0xffff0000, v114
	v_mul_f32_e32 v112, v36, v28
	v_fma_f32 v28, v1, v47, v34
	v_add_f32_e32 v28, v28, v35
	v_pk_mul_f32 v[34:35], v[44:45], v[50:51]
	v_pk_mul_f32 v[38:39], v[86:87], v[92:93]
	v_mov_b32_e32 v36, v48
	v_mov_b32_e32 v37, v34
	v_mov_b32_e32 v40, v54
	v_mov_b32_e32 v41, v38
	v_and_b32_e32 v24, 0xffff0000, v24
	v_pk_mul_f32 v[36:37], v[66:67], v[36:37]
	v_pk_mul_f32 v[40:41], v[6:7], v[40:41]
	v_and_b32_e32 v125, 0xffff0000, v113
	v_mul_f32_e32 v113, v28, v24
	v_and_b32_e32 v43, 0xffff0000, v29
	v_lshlrev_b32_e32 v42, 16, v29
	v_mov_b32_e32 v54, v49
	v_mov_b32_e32 v28, v36
	v_mov_b32_e32 v29, v40
	v_pk_fma_f32 v[28:29], v[10:11], v[54:55], v[28:29]
	v_mov_b32_e32 v40, v37
	v_pk_add_f32 v[28:29], v[28:29], v[40:41]
	v_mul_f32_e32 v46, v112, v112
	v_pk_mul_f32 v[28:29], v[28:29], v[42:43]
	v_fmac_f32_e32 v46, v108, v108
	v_pk_mul_f32 v[36:37], v[28:29], v[28:29]
	v_pk_mul_f32 v[34:35], v[68:69], v[34:35]
	v_add_f32_e32 v24, v36, v46
	v_add_f32_e32 v46, v37, v24
	v_pk_mul_f32 v[36:37], v[70:71], v[38:39]
	v_and_b32_e32 v39, 0xffff0000, v25
	v_lshlrev_b32_e32 v38, 16, v25
	v_mov_b32_e32 v24, v34
	v_mov_b32_e32 v25, v36
	v_pk_fma_f32 v[24:25], v[2:3], v[54:55], v[24:25]
	v_mov_b32_e32 v36, v35
	v_pk_add_f32 v[24:25], v[24:25], v[36:37]
	v_mul_f32_e32 v47, v113, v113
	v_pk_mul_f32 v[24:25], v[24:25], v[38:39]
	v_fmac_f32_e32 v47, v109, v109
	v_pk_mul_f32 v[34:35], v[24:25], v[24:25]
	v_pk_mul_f32 v[38:39], v[98:99], v[100:101]
	v_add_f32_e32 v34, v34, v47
	v_add_f32_e32 v47, v35, v34
	v_pk_mul_f32 v[34:35], v[94:95], v[96:97]
	v_mov_b32_e32 v36, v52
	v_mov_b32_e32 v37, v34
	v_mov_b32_e32 v40, v88
	v_mov_b32_e32 v41, v38
	v_pk_mul_f32 v[36:37], v[72:73], v[36:37]
	v_pk_mul_f32 v[40:41], v[16:17], v[40:41]
	v_mov_b32_e32 v88, v53
	v_mov_b32_e32 v44, v36
	v_mov_b32_e32 v45, v40
	v_pk_fma_f32 v[44:45], v[20:21], v[88:89], v[44:45]
	v_mov_b32_e32 v40, v37
	v_and_b32_e32 v43, 0xffff0000, v30
	v_lshlrev_b32_e32 v42, 16, v30
	v_pk_add_f32 v[36:37], v[44:45], v[40:41]
	v_pk_mul_f32 v[34:35], v[74:75], v[34:35]
	v_pk_mul_f32 v[36:37], v[36:37], v[42:43]
	v_pk_mul_f32 v[38:39], v[76:77], v[38:39]
	v_pk_mul_f32 v[40:41], v[36:37], v[36:37]
	v_mov_b32_e32 v42, v34
	v_mov_b32_e32 v43, v38
	v_add_f32_e32 v30, v40, v46
	v_pk_fma_f32 v[42:43], v[12:13], v[88:89], v[42:43]
	v_mov_b32_e32 v38, v35
	v_add_f32_e32 v48, v41, v30
	v_and_b32_e32 v41, 0xffff0000, v26
	v_lshlrev_b32_e32 v40, 16, v26
	v_pk_add_f32 v[34:35], v[42:43], v[38:39]
	v_pk_mul_f32 v[42:43], v[120:121], v[124:125]
	v_pk_mul_f32 v[34:35], v[34:35], v[40:41]
	v_mov_b32_e32 v40, v90
	v_pk_mul_f32 v[38:39], v[34:35], v[34:35]
	v_mov_b32_e32 v44, v32
	v_add_f32_e32 v26, v38, v47
	v_add_f32_e32 v49, v39, v26
	v_pk_mul_f32 v[38:39], v[110:111], v[116:117]
	v_mov_b32_e32 v45, v42
	v_mov_b32_e32 v41, v38
	v_pk_mul_f32 v[40:41], v[78:79], v[40:41]
	v_pk_mul_f32 v[44:45], v[18:19], v[44:45]
	v_and_b32_e32 v47, 0xffff0000, v31
	v_lshlrev_b32_e32 v46, 16, v31
	v_mov_b32_e32 v32, v91
	v_mov_b32_e32 v30, v40
	v_mov_b32_e32 v31, v44
	v_pk_fma_f32 v[30:31], v[22:23], v[32:33], v[30:31]
	v_mov_b32_e32 v44, v41
	v_pk_add_f32 v[30:31], v[30:31], v[44:45]
	v_pk_mul_f32 v[38:39], v[80:81], v[38:39]
	v_pk_mul_f32 v[30:31], v[30:31], v[46:47]
	s_nop 0
	v_pk_mul_f32 v[40:41], v[30:31], v[30:31]
	s_nop 0
	v_add_f32_e32 v26, v40, v48
	v_add_f32_e32 v26, v41, v26
	s_waitcnt lgkmcnt(0)
	s_nop 1
	v_add_f32_dpp v26, v26, v26 quad_perm:[1,0,3,2] row_mask:0xf bank_mask:0xf
	s_waitcnt lgkmcnt(0)
	s_nop 1
	v_add_f32_dpp v26, v26, v26 quad_perm:[2,3,0,1] row_mask:0xf bank_mask:0xf
	s_waitcnt lgkmcnt(0)
	s_nop 1
	v_add_f32_dpp v26, v26, v26 row_half_mirror row_mask:0xf bank_mask:0xf
	s_waitcnt lgkmcnt(0)
	s_nop 1
	v_add_f32_dpp v26, v26, v26 row_mirror row_mask:0xf bank_mask:0xf
	s_nop 1
	v_mov_b32_e32 v40, v26
	s_nop 1
	v_permlane16_swap_b32_e32 v40, v26
	s_waitcnt lgkmcnt(0)
	v_add_f32_e32 v26, v26, v40
	v_fmamk_f32 v26, v26, 0x3b800000, v244
	v_cmp_gt_f32_e32 vcc, s7, v26
	v_mul_f32_e32 v40, 0x4b800000, v26
	s_nop 0
	v_cndmask_b32_e32 v26, v26, v40, vcc
	v_rsq_f32_e32 v26, v26
	s_nop 0
	v_mul_f32_e32 v40, 0x45800000, v26
	v_cndmask_b32_e32 v26, v26, v40, vcc
	v_mul_f32_e32 v29, v29, v26
	v_mul_f32_e32 v36, v36, v26
	v_mul_f32_e32 v40, v108, v26
	v_mul_f32_e32 v41, v112, v26
	v_mul_f32_e32 v44, v28, v26
	v_mul_f32_e32 v37, v37, v26
	v_mul_f32_e32 v45, v30, v26
	v_cvt_pk_bf16_f32 v28, v40, v41
	v_cvt_pk_bf16_f32 v29, v44, v29
	v_cvt_pk_bf16_f32 v30, v36, v37
	v_add_co_u32_e32 v36, vcc, s35, v84
	v_mul_f32_e32 v26, v31, v26
	s_nop 0
	v_addc_co_u32_e32 v37, vcc, 0, v85, vcc
	v_cvt_pk_bf16_f32 v31, v45, v26
	global_store_dwordx4 v[36:37], v[28:31], off
	v_mov_b32_e32 v26, v38
	s_nop 0
	v_pk_mul_f32 v[28:29], v[82:83], v[42:43]
	v_and_b32_e32 v31, 0xffff0000, v27
	v_lshlrev_b32_e32 v30, 16, v27
	v_mov_b32_e32 v27, v28
	v_pk_fma_f32 v[26:27], v[14:15], v[32:33], v[26:27]
	v_mov_b32_e32 v28, v39
	v_pk_add_f32 v[26:27], v[26:27], v[28:29]
	s_nop 0
	v_pk_mul_f32 v[26:27], v[26:27], v[30:31]
	s_nop 0
	v_pk_mul_f32 v[28:29], v[26:27], v[26:27]
	s_nop 0
	v_add_f32_e32 v28, v28, v49
	v_add_f32_e32 v28, v29, v28
	s_waitcnt lgkmcnt(0)
	s_nop 1
	v_add_f32_dpp v28, v28, v28 quad_perm:[1,0,3,2] row_mask:0xf bank_mask:0xf
	s_waitcnt lgkmcnt(0)
	s_nop 1
	v_add_f32_dpp v28, v28, v28 quad_perm:[2,3,0,1] row_mask:0xf bank_mask:0xf
	s_waitcnt lgkmcnt(0)
	s_nop 1
	v_add_f32_dpp v28, v28, v28 row_half_mirror row_mask:0xf bank_mask:0xf
	s_waitcnt lgkmcnt(0)
	s_nop 1
	v_add_f32_dpp v28, v28, v28 row_mirror row_mask:0xf bank_mask:0xf
	s_nop 1
	v_mov_b32_e32 v29, v28
	s_nop 1
	v_permlane16_swap_b32_e32 v29, v28
	s_waitcnt lgkmcnt(0)
	v_add_f32_e32 v28, v28, v29
	v_fmamk_f32 v28, v28, 0x3b800000, v244
	v_cmp_gt_f32_e32 vcc, s7, v28
	v_mul_f32_e32 v29, 0x4b800000, v28
	s_nop 0
	v_cndmask_b32_e32 v28, v28, v29, vcc
	v_rsq_f32_e32 v28, v28
	s_nop 0
	v_mul_f32_e32 v29, 0x45800000, v28
	v_cndmask_b32_e32 v28, v28, v29, vcc
	v_mul_f32_e32 v25, v25, v28
	v_mul_f32_e32 v27, v27, v28
	v_mul_f32_e32 v29, v109, v28
	v_mul_f32_e32 v30, v113, v28
	v_mul_f32_e32 v31, v24, v28
	v_mul_f32_e32 v32, v34, v28
	v_mul_f32_e32 v33, v35, v28
	v_mul_f32_e32 v34, v26, v28
	v_cvt_pk_bf16_f32 v24, v29, v30
	v_cvt_pk_bf16_f32 v25, v31, v25
	v_cvt_pk_bf16_f32 v26, v32, v33
	v_cvt_pk_bf16_f32 v27, v34, v27
	global_store_dwordx4 v[36:37], v[24:27], off offset:2048
	s_cbranch_scc1 .LBB0_227

.LBB0_437:
	v_and_b32_e32 v113, 64, v245
	v_xor_b32_e32 v112, 16, v245
	v_add_u32_e32 v113, 64, v113
	v_cmp_lt_i32_e32 vcc, v112, v113
	v_mul_f32_e32 v114, v167, v167
	v_fmac_f32_e32 v114, v166, v166
	v_cndmask_b32_e32 v112, v245, v112, vcc
	v_lshlrev_b32_e32 v240, 2, v112
	v_mul_f32_e32 v112, v165, v165
	v_fmac_f32_e32 v112, v164, v164
	v_add_f32_e32 v112, v112, v114
	v_mul_f32_e32 v114, v161, v161
	v_mul_f32_e32 v115, v163, v163
	v_fmac_f32_e32 v114, v160, v160
	v_fmac_f32_e32 v115, v162, v162
	v_add_f32_e32 v114, v114, v115
	v_add_f32_e32 v112, v112, v114
	v_mul_f32_e32 v114, v129, v129
	v_mul_f32_e32 v115, v131, v131
	v_fmac_f32_e32 v114, v128, v128
	v_fmac_f32_e32 v115, v130, v130
	v_add_f32_e32 v114, v114, v115
	v_add_f32_e32 v112, v112, v114
	v_mul_f32_e32 v114, v125, v125
	v_mul_f32_e32 v115, v127, v127
	v_fmac_f32_e32 v114, v124, v124
	v_fmac_f32_e32 v115, v126, v126
	v_add_f32_e32 v114, v114, v115
	v_add_f32_e32 v112, v112, v114
	s_nop 1
	v_mov_b32_e32 v114, v112
	s_nop 1
	v_permlane16_swap_b32_e32 v114, v112
	v_xor_b32_e32 v115, 32, v245
	v_cmp_lt_i32_e32 vcc, v115, v113
	v_mov_b32_e32 v234, v237
	s_waitcnt lgkmcnt(0)
	v_add_f32_e32 v114, v112, v114
	v_cndmask_b32_e32 v113, v245, v115, vcc
	v_lshlrev_b32_e32 v241, 2, v113
	s_nop 1
	v_mov_b32_e32 v115, v114
	s_nop 1
	v_permlane32_swap_b32_e32 v115, v114
	v_mov_b32_e32 v112, v236
	s_nop 0
	v_cmp_eq_u32_e64 s[38:39], 0, v112
	v_lshl_add_u32 v113, v234, 4, s97
	s_and_saveexec_b64 s[2:3], s[38:39]
	s_cbranch_execz .LBB0_439
	s_waitcnt lgkmcnt(0)
	v_add_f32_e32 v114, v114, v115
	ds_write_b32 v113, v114
.LBB0_439:
	s_or_b64 exec, exec, s[2:3]
	v_mul_f32_e32 v114, v109, v109
	s_waitcnt lgkmcnt(0)
	v_mul_f32_e32 v115, v111, v111
	v_fmac_f32_e32 v114, v108, v108
	v_fmac_f32_e32 v115, v110, v110
	v_add_f32_e32 v114, v114, v115
	v_mul_f32_e32 v115, v105, v105
	v_mul_f32_e32 v116, v107, v107
	v_fmac_f32_e32 v115, v104, v104
	v_fmac_f32_e32 v116, v106, v106
	v_add_f32_e32 v115, v115, v116
	v_add_f32_e32 v114, v114, v115
	v_mul_f32_e32 v115, v101, v101
	v_mul_f32_e32 v116, v103, v103
	v_fmac_f32_e32 v115, v100, v100
	v_fmac_f32_e32 v116, v102, v102
	v_add_f32_e32 v115, v115, v116
	v_add_f32_e32 v114, v114, v115
	v_mul_f32_e32 v115, v97, v97
	v_mul_f32_e32 v116, v99, v99
	v_fmac_f32_e32 v115, v96, v96
	v_fmac_f32_e32 v116, v98, v98
	v_add_f32_e32 v115, v115, v116
	v_add_f32_e32 v114, v114, v115
	s_nop 1
	v_mov_b32_e32 v115, v114
	s_nop 1
	v_permlane16_swap_b32_e32 v115, v114
	s_waitcnt lgkmcnt(0)
	v_add_f32_e32 v114, v114, v115
	s_nop 1
	v_mov_b32_e32 v115, v114
	s_nop 1
	v_permlane32_swap_b32_e32 v115, v114
	s_and_saveexec_b64 s[2:3], s[38:39]
	s_cbranch_execz .LBB0_441
	s_waitcnt lgkmcnt(0)
	v_add_f32_e32 v114, v114, v115
	ds_write_b32 v113, v114 offset:256
.LBB0_441:
	s_or_b64 exec, exec, s[2:3]
	v_mul_f32_e32 v114, v93, v93
	s_waitcnt lgkmcnt(0)
	v_mul_f32_e32 v115, v95, v95
	v_fmac_f32_e32 v114, v92, v92
	v_fmac_f32_e32 v115, v94, v94
	v_add_f32_e32 v114, v114, v115
	v_mul_f32_e32 v115, v89, v89
	v_mul_f32_e32 v116, v91, v91
	v_fmac_f32_e32 v115, v88, v88
	v_fmac_f32_e32 v116, v90, v90
	v_add_f32_e32 v115, v115, v116
	v_add_f32_e32 v114, v114, v115
	v_mul_f32_e32 v115, v85, v85
	v_mul_f32_e32 v116, v87, v87
	v_fmac_f32_e32 v115, v84, v84
	v_fmac_f32_e32 v116, v86, v86
	v_add_f32_e32 v115, v115, v116
	v_add_f32_e32 v114, v114, v115
	v_mul_f32_e32 v115, v81, v81
	v_mul_f32_e32 v116, v83, v83
	v_fmac_f32_e32 v115, v80, v80
	v_fmac_f32_e32 v116, v82, v82
	v_add_f32_e32 v115, v115, v116
	v_add_f32_e32 v114, v114, v115
	s_nop 1
	v_mov_b32_e32 v115, v114
	s_nop 1
	v_permlane16_swap_b32_e32 v115, v114
	s_waitcnt lgkmcnt(0)
	v_add_f32_e32 v114, v114, v115
	s_nop 1
	v_mov_b32_e32 v115, v114
	s_nop 1
	v_permlane32_swap_b32_e32 v115, v114
	s_and_saveexec_b64 s[2:3], s[38:39]
	s_cbranch_execz .LBB0_443
	s_waitcnt lgkmcnt(0)
	v_add_f32_e32 v114, v114, v115
	ds_write_b32 v113, v114 offset:512
.LBB0_443:
	s_or_b64 exec, exec, s[2:3]
	v_mul_f32_e32 v114, v77, v77
	s_waitcnt lgkmcnt(0)
	v_mul_f32_e32 v115, v79, v79
	v_fmac_f32_e32 v114, v76, v76
	v_fmac_f32_e32 v115, v78, v78
	v_add_f32_e32 v114, v114, v115
	v_mul_f32_e32 v115, v73, v73
	v_mul_f32_e32 v116, v75, v75
	v_fmac_f32_e32 v115, v72, v72
	v_fmac_f32_e32 v116, v74, v74
	v_add_f32_e32 v115, v115, v116
	v_add_f32_e32 v114, v114, v115
	v_mul_f32_e32 v115, v69, v69
	v_mul_f32_e32 v116, v71, v71
	v_fmac_f32_e32 v115, v68, v68
	v_fmac_f32_e32 v116, v70, v70
	v_add_f32_e32 v115, v115, v116
	v_add_f32_e32 v114, v114, v115
	v_mul_f32_e32 v115, v65, v65
	v_mul_f32_e32 v116, v67, v67
	v_fmac_f32_e32 v115, v64, v64
	v_fmac_f32_e32 v116, v66, v66
	v_add_f32_e32 v115, v115, v116
	v_add_f32_e32 v114, v114, v115
	s_nop 1
	v_mov_b32_e32 v115, v114
	s_nop 1
	v_permlane16_swap_b32_e32 v115, v114
	s_waitcnt lgkmcnt(0)
	v_add_f32_e32 v114, v114, v115
	s_nop 1
	v_mov_b32_e32 v115, v114
	s_nop 1
	v_permlane32_swap_b32_e32 v115, v114
	s_and_saveexec_b64 s[2:3], s[38:39]
	s_cbranch_execz .LBB0_445
	s_waitcnt lgkmcnt(0)
	v_add_f32_e32 v114, v114, v115
	ds_write_b32 v113, v114 offset:768
.LBB0_445:
	s_or_b64 exec, exec, s[2:3]
	v_mul_f32_e32 v114, v61, v61
	s_waitcnt lgkmcnt(0)
	v_mul_f32_e32 v115, v63, v63
	v_fmac_f32_e32 v114, v60, v60
	v_fmac_f32_e32 v115, v62, v62
	v_add_f32_e32 v114, v114, v115
	v_mul_f32_e32 v115, v57, v57
	v_mul_f32_e32 v116, v59, v59
	v_fmac_f32_e32 v115, v56, v56
	v_fmac_f32_e32 v116, v58, v58
	v_add_f32_e32 v115, v115, v116
	v_add_f32_e32 v114, v114, v115
	v_mul_f32_e32 v115, v53, v53
	v_mul_f32_e32 v116, v55, v55
	v_fmac_f32_e32 v115, v52, v52
	v_fmac_f32_e32 v116, v54, v54
	v_add_f32_e32 v115, v115, v116
	v_add_f32_e32 v114, v114, v115
	v_mul_f32_e32 v115, v49, v49
	v_mul_f32_e32 v116, v51, v51
	v_fmac_f32_e32 v115, v48, v48
	v_fmac_f32_e32 v116, v50, v50
	v_add_f32_e32 v115, v115, v116
	v_add_f32_e32 v114, v114, v115
	s_nop 1
	v_mov_b32_e32 v115, v114
	s_nop 1
	v_permlane16_swap_b32_e32 v115, v114
	s_waitcnt lgkmcnt(0)
	v_add_f32_e32 v114, v114, v115
	s_nop 1
	v_mov_b32_e32 v115, v114
	s_nop 1
	v_permlane32_swap_b32_e32 v115, v114
	s_and_saveexec_b64 s[2:3], s[38:39]
	s_cbranch_execz .LBB0_447
	s_waitcnt lgkmcnt(0)
	v_add_f32_e32 v114, v114, v115
	ds_write_b32 v113, v114 offset:2048
.LBB0_447:
	s_or_b64 exec, exec, s[2:3]
	v_mul_f32_e32 v114, v45, v45
	s_waitcnt lgkmcnt(0)
	v_mul_f32_e32 v115, v47, v47
	v_fmac_f32_e32 v114, v44, v44
	v_fmac_f32_e32 v115, v46, v46
	v_add_f32_e32 v114, v114, v115
	v_mul_f32_e32 v115, v41, v41
	v_mul_f32_e32 v116, v43, v43
	v_fmac_f32_e32 v115, v40, v40
	v_fmac_f32_e32 v116, v42, v42
	v_add_f32_e32 v115, v115, v116
	v_add_f32_e32 v114, v114, v115
	v_mul_f32_e32 v115, v37, v37
	v_mul_f32_e32 v116, v39, v39
	v_fmac_f32_e32 v115, v36, v36
	v_fmac_f32_e32 v116, v38, v38
	v_add_f32_e32 v115, v115, v116
	v_add_f32_e32 v114, v114, v115
	v_mul_f32_e32 v115, v33, v33
	v_mul_f32_e32 v116, v35, v35
	v_fmac_f32_e32 v115, v32, v32
	v_fmac_f32_e32 v116, v34, v34
	v_add_f32_e32 v115, v115, v116
	v_add_f32_e32 v114, v114, v115
	s_nop 1
	v_mov_b32_e32 v115, v114
	s_nop 1
	v_permlane16_swap_b32_e32 v115, v114
	s_waitcnt lgkmcnt(0)
	v_add_f32_e32 v114, v114, v115
	s_nop 1
	v_mov_b32_e32 v115, v114
	s_nop 1
	v_permlane32_swap_b32_e32 v115, v114
	s_and_saveexec_b64 s[2:3], s[38:39]
	s_cbranch_execz .LBB0_449
	s_waitcnt lgkmcnt(0)
	v_add_f32_e32 v114, v114, v115
	ds_write_b32 v113, v114 offset:2304
.LBB0_449:
	s_or_b64 exec, exec, s[2:3]
	v_mul_f32_e32 v114, v29, v29
	s_waitcnt lgkmcnt(0)
	v_mul_f32_e32 v115, v31, v31
	v_fmac_f32_e32 v114, v28, v28
	v_fmac_f32_e32 v115, v30, v30
	v_add_f32_e32 v114, v114, v115
	v_mul_f32_e32 v115, v25, v25
	v_mul_f32_e32 v116, v27, v27
	v_fmac_f32_e32 v115, v24, v24
	v_fmac_f32_e32 v116, v26, v26
	v_add_f32_e32 v115, v115, v116
	v_add_f32_e32 v114, v114, v115
	v_mul_f32_e32 v115, v21, v21
	v_mul_f32_e32 v116, v23, v23
	v_fmac_f32_e32 v115, v20, v20
	v_fmac_f32_e32 v116, v22, v22
	v_add_f32_e32 v115, v115, v116
	v_add_f32_e32 v114, v114, v115
	v_mul_f32_e32 v115, v17, v17
	v_mul_f32_e32 v116, v19, v19
	v_fmac_f32_e32 v115, v16, v16
	v_fmac_f32_e32 v116, v18, v18
	v_add_f32_e32 v115, v115, v116
	v_add_f32_e32 v114, v114, v115
	s_nop 1
	v_mov_b32_e32 v115, v114
	s_nop 1
	v_permlane16_swap_b32_e32 v115, v114
	s_waitcnt lgkmcnt(0)
	v_add_f32_e32 v114, v114, v115
	s_nop 1
	v_mov_b32_e32 v115, v114
	s_nop 1
	v_permlane32_swap_b32_e32 v115, v114
	s_and_saveexec_b64 s[2:3], s[38:39]
	s_cbranch_execz .LBB0_451
	s_waitcnt lgkmcnt(0)
	v_add_f32_e32 v114, v114, v115
	ds_write_b32 v113, v114 offset:2560
.LBB0_451:
	s_or_b64 exec, exec, s[2:3]
	v_mul_f32_e32 v114, v13, v13
	s_waitcnt lgkmcnt(0)
	v_mul_f32_e32 v115, v15, v15
	v_fmac_f32_e32 v114, v12, v12
	v_fmac_f32_e32 v115, v14, v14
	v_add_f32_e32 v114, v114, v115
	v_mul_f32_e32 v115, v9, v9
	v_mul_f32_e32 v116, v11, v11
	v_fmac_f32_e32 v115, v8, v8
	v_fmac_f32_e32 v116, v10, v10
	v_add_f32_e32 v115, v115, v116
	v_add_f32_e32 v114, v114, v115
	v_mul_f32_e32 v115, v5, v5
	v_mul_f32_e32 v116, v7, v7
	v_fmac_f32_e32 v115, v4, v4
	v_fmac_f32_e32 v116, v6, v6
	v_add_f32_e32 v115, v115, v116
	v_add_f32_e32 v114, v114, v115
	v_mul_f32_e32 v115, v1, v1
	v_mul_f32_e32 v116, v3, v3
	v_fmac_f32_e32 v115, v0, v0
	v_fmac_f32_e32 v116, v2, v2
	v_add_f32_e32 v115, v115, v116
	v_add_f32_e32 v114, v114, v115
	s_nop 1
	v_mov_b32_e32 v115, v114
	s_nop 1
	v_permlane16_swap_b32_e32 v115, v114
	s_waitcnt lgkmcnt(0)
	v_add_f32_e32 v114, v114, v115
	s_nop 1
	v_mov_b32_e32 v115, v114
	s_nop 1
	v_permlane32_swap_b32_e32 v115, v114
	s_and_saveexec_b64 s[2:3], s[38:39]
	s_cbranch_execz .LBB0_453
	s_waitcnt lgkmcnt(0)
	v_add_f32_e32 v114, v114, v115
	ds_write_b32 v113, v114 offset:2816

.LBB0_475:
	s_lshl_b32 s2, s28, 8
	s_or_b32 s2, s2, s73
	v_add_u32_e32 v140, s2, v232
	v_ashrrev_i32_e32 v141, 31, v140
	s_waitcnt vmcnt(0) lgkmcnt(0)
	s_barrier
	v_lshl_add_u64 v[144:145], v[140:141], 2, s[26:27]
	global_load_dwordx4 v[152:155], v[144:145], off offset:16
	global_load_dwordx4 v[156:159], v[144:145], off
	global_load_dwordx4 v[140:143], v[144:145], off offset:528
	s_nop 0
	global_load_dwordx4 v[144:147], v[144:145], off offset:512
	v_add_u32_e32 v247, s72, v234
	v_lshl_add_u32 v214, v247, 2, 0
	v_add_u32_e32 v248, 0x21000, v214
	ds_read_b32 v214, v248
	v_add_u32_e32 v216, s91, v247
	v_ashrrev_i32_e32 v217, 31, v216
	v_lshlrev_b64 v[234:235], 6, v[216:217]
	s_add_u32 s48, s62, s48
	s_waitcnt lgkmcnt(0)
	v_pk_mul_f32 v[164:165], v[164:165], v[214:215] op_sel_hi:[1,0]
	v_pk_mul_f32 v[166:167], v[166:167], v[214:215] op_sel_hi:[1,0]
	v_pk_mul_f32 v[162:163], v[162:163], v[214:215] op_sel_hi:[1,0]
	v_pk_mul_f32 v[160:161], v[160:161], v[214:215] op_sel_hi:[1,0]
	s_waitcnt vmcnt(0)
	v_lshlrev_b32_e32 v215, 16, v204
	v_and_b32_e32 v204, 0xffff0000, v204
	s_addc_u32 s49, s63, s49
	s_add_u32 s78, s62, s78
	s_addc_u32 s79, s63, s79
	v_pk_mul_f32 v[160:161], v[152:153], v[160:161]
	v_pk_mul_f32 v[164:165], v[156:157], v[164:165]
	v_pk_mul_f32 v[166:167], v[158:159], v[166:167]
	v_add_f32_e32 v165, v165, v204
	v_lshlrev_b32_e32 v204, 16, v205
	v_add_f32_e32 v204, v166, v204
	v_and_b32_e32 v166, 0xffff0000, v205
	v_add_f32_e32 v205, v167, v166
	v_lshlrev_b32_e32 v166, 16, v206
	v_add_f32_e32 v164, v164, v215
	v_add_f32_e32 v215, v160, v166
	v_and_b32_e32 v160, 0xffff0000, v206
	v_pk_mul_f32 v[162:163], v[154:155], v[162:163]
	v_add_f32_e32 v206, v161, v160
	v_lshlrev_b32_e32 v160, 16, v207
	v_add_f32_e32 v216, v162, v160
	v_and_b32_e32 v160, 0xffff0000, v207
	v_add_f32_e32 v207, v163, v160
	v_mul_f32_e32 v160, v165, v165
	v_mul_f32_e32 v161, v205, v205
	v_fmac_f32_e32 v160, v164, v164
	v_fmac_f32_e32 v161, v204, v204
	v_add_f32_e32 v160, v160, v161
	v_mul_f32_e32 v161, v206, v206
	v_fmac_f32_e32 v161, v215, v215
	v_add_f32_e32 v160, v161, v160
	v_mul_f32_e32 v161, v207, v207
	v_fmac_f32_e32 v161, v216, v216
	v_add_f32_e32 v217, v161, v160
	v_lshl_add_u64 v[162:163], s[48:49], 0, v[234:235]
	v_lshlrev_b64 v[160:161], 1, v[232:233]
	v_lshl_add_u64 v[166:167], v[162:163], 0, v[160:161]
	v_cvt_pk_bf16_f32 v162, v164, v165
	v_cvt_pk_bf16_f32 v163, v204, v205
	v_cvt_pk_bf16_f32 v164, v215, v206
	v_cvt_pk_bf16_f32 v165, v216, v207
	global_store_dwordx4 v[166:167], v[162:165], off nt
	v_pk_mul_f32 v[128:129], v[128:129], v[214:215] op_sel_hi:[1,0]
	v_pk_mul_f32 v[126:127], v[126:127], v[214:215] op_sel_hi:[1,0]
	v_pk_mul_f32 v[162:163], v[124:125], v[214:215] op_sel_hi:[1,0]
	v_pk_mul_f32 v[128:129], v[144:145], v[128:129]
	v_pk_mul_f32 v[124:125], v[142:143], v[126:127]
	v_pk_mul_f32 v[126:127], v[140:141], v[162:163]
	v_lshlrev_b32_e32 v162, 16, v200
	v_pk_mul_f32 v[130:131], v[130:131], v[214:215] op_sel_hi:[1,0]
	v_add_f32_e32 v162, v128, v162
	v_and_b32_e32 v128, 0xffff0000, v200
	v_pk_mul_f32 v[130:131], v[146:147], v[130:131]
	v_add_f32_e32 v163, v129, v128
	v_lshlrev_b32_e32 v128, 16, v201
	v_add_f32_e32 v130, v130, v128
	v_and_b32_e32 v128, 0xffff0000, v201
	v_add_f32_e32 v131, v131, v128
	v_lshlrev_b32_e32 v128, 16, v202
	v_add_f32_e32 v126, v126, v128
	v_and_b32_e32 v128, 0xffff0000, v202
	v_add_f32_e32 v127, v127, v128
	v_lshlrev_b32_e32 v128, 16, v203
	v_add_f32_e32 v164, v124, v128
	v_and_b32_e32 v124, 0xffff0000, v203
	v_add_f32_e32 v165, v125, v124
	v_mul_f32_e32 v124, v163, v163
	v_mul_f32_e32 v125, v131, v131
	v_fmac_f32_e32 v124, v162, v162
	v_fmac_f32_e32 v125, v130, v130
	v_add_f32_e32 v124, v124, v125
	v_mul_f32_e32 v125, v127, v127
	v_fmac_f32_e32 v125, v126, v126
	v_add_f32_e32 v124, v125, v124
	v_mul_f32_e32 v125, v165, v165
	v_fmac_f32_e32 v125, v164, v164
	v_add_f32_e32 v124, v125, v124
	v_add_f32_e32 v166, v217, v124
	v_lshl_add_u64 v[124:125], s[78:79], 0, v[234:235]
	v_lshl_add_u64 v[128:129], v[124:125], 0, v[160:161]
	v_cvt_pk_bf16_f32 v124, v162, v163
	v_cvt_pk_bf16_f32 v125, v130, v131
	v_cvt_pk_bf16_f32 v126, v126, v127
	v_cvt_pk_bf16_f32 v127, v164, v165
	global_store_dwordx4 v[128:129], v[124:127], off nt
	s_nop 1
	v_mov_b32_e32 v124, v166
	s_nop 1
	v_permlane16_swap_b32_e32 v124, v166
	s_waitcnt lgkmcnt(0)
	v_add_f32_e32 v124, v166, v124
	s_nop 1
	v_mov_b32_e32 v125, v124
	s_nop 1
	v_permlane32_swap_b32_e32 v125, v124
	s_and_saveexec_b64 s[2:3], s[38:39]
	s_cbranch_execz .LBB0_477
	v_lshl_add_u32 v126, v247, 4, s96
	s_waitcnt lgkmcnt(0)
	v_add_f32_e32 v124, v124, v125
	ds_write_b32 v126, v124
.LBB0_477:
	s_or_b64 exec, exec, s[2:3]
	ds_read_b32 v126, v248 offset:64
	s_waitcnt lgkmcnt(1)
	v_lshlrev_b32_e32 v125, 16, v196
	v_add_u32_e32 v124, 16, v247
	v_add_u32_e32 v128, s91, v124
	v_ashrrev_i32_e32 v129, 31, v128
	s_waitcnt lgkmcnt(0)
	v_pk_mul_f32 v[108:109], v[108:109], v[126:127] op_sel_hi:[1,0]
	v_pk_mul_f32 v[110:111], v[110:111], v[126:127] op_sel_hi:[1,0]
	v_pk_mul_f32 v[108:109], v[156:157], v[108:109]
	v_pk_mul_f32 v[110:111], v[158:159], v[110:111]
	v_add_f32_e32 v125, v108, v125
	v_and_b32_e32 v108, 0xffff0000, v196
	v_pk_mul_f32 v[106:107], v[106:107], v[126:127] op_sel_hi:[1,0]
	v_pk_mul_f32 v[104:105], v[104:105], v[126:127] op_sel_hi:[1,0]
	v_add_f32_e32 v127, v109, v108
	v_lshlrev_b32_e32 v108, 16, v197
	v_add_f32_e32 v110, v110, v108
	v_and_b32_e32 v108, 0xffff0000, v197
	v_pk_mul_f32 v[104:105], v[152:153], v[104:105]
	v_add_f32_e32 v111, v111, v108
	v_lshlrev_b32_e32 v108, 16, v198
	v_add_f32_e32 v130, v104, v108
	v_and_b32_e32 v104, 0xffff0000, v198
	v_pk_mul_f32 v[106:107], v[154:155], v[106:107]
	v_add_f32_e32 v131, v105, v104
	v_lshlrev_b32_e32 v104, 16, v199
	v_add_f32_e32 v162, v106, v104
	v_and_b32_e32 v104, 0xffff0000, v199
	v_add_f32_e32 v107, v107, v104
	v_mul_f32_e32 v104, v127, v127
	v_mul_f32_e32 v105, v111, v111
	v_fmac_f32_e32 v104, v125, v125
	v_fmac_f32_e32 v105, v110, v110
	v_add_f32_e32 v104, v104, v105
	v_mul_f32_e32 v105, v131, v131
	v_fmac_f32_e32 v105, v130, v130
	v_add_f32_e32 v104, v105, v104
	v_mul_f32_e32 v105, v107, v107
	v_lshlrev_b64 v[128:129], 6, v[128:129]
	v_fmac_f32_e32 v105, v162, v162
	v_add_f32_e32 v163, v105, v104
	v_lshl_add_u64 v[104:105], s[48:49], 0, v[128:129]
	v_pk_mul_f32 v[100:101], v[100:101], v[126:127] op_sel_hi:[1,0]
	v_lshl_add_u64 v[108:109], v[104:105], 0, v[160:161]
	v_cvt_pk_bf16_f32 v104, v125, v127
	v_cvt_pk_bf16_f32 v105, v110, v111
	v_pk_mul_f32 v[100:101], v[144:145], v[100:101]
	v_lshlrev_b32_e32 v110, 16, v192
	v_pk_mul_f32 v[102:103], v[102:103], v[126:127] op_sel_hi:[1,0]
	v_add_f32_e32 v100, v100, v110
	v_and_b32_e32 v110, 0xffff0000, v192
	v_pk_mul_f32 v[102:103], v[146:147], v[102:103]
	v_add_f32_e32 v101, v101, v110
	v_lshlrev_b32_e32 v110, 16, v193
	v_pk_mul_f32 v[96:97], v[96:97], v[126:127] op_sel_hi:[1,0]
	v_add_f32_e32 v110, v102, v110
	v_and_b32_e32 v102, 0xffff0000, v193
	v_pk_mul_f32 v[96:97], v[140:141], v[96:97]
	v_add_f32_e32 v111, v103, v102
	v_lshlrev_b32_e32 v102, 16, v194
	v_pk_mul_f32 v[98:99], v[98:99], v[126:127] op_sel_hi:[1,0]
	v_add_f32_e32 v125, v96, v102
	v_and_b32_e32 v96, 0xffff0000, v194
	v_pk_mul_f32 v[98:99], v[142:143], v[98:99]
	v_add_f32_e32 v126, v97, v96
	v_lshlrev_b32_e32 v96, 16, v195
	v_add_f32_e32 v127, v98, v96
	v_and_b32_e32 v96, 0xffff0000, v195
	v_cvt_pk_bf16_f32 v106, v130, v131
	v_add_f32_e32 v130, v99, v96
	v_mul_f32_e32 v96, v101, v101
	v_mul_f32_e32 v97, v111, v111
	v_fmac_f32_e32 v96, v100, v100
	v_fmac_f32_e32 v97, v110, v110
	v_add_f32_e32 v96, v96, v97
	v_mul_f32_e32 v97, v126, v126
	v_fmac_f32_e32 v97, v125, v125
	v_add_f32_e32 v96, v97, v96
	v_mul_f32_e32 v97, v130, v130
	v_fmac_f32_e32 v97, v127, v127
	v_add_f32_e32 v96, v97, v96
	v_add_f32_e32 v99, v163, v96
	s_nop 1
	v_mov_b32_e32 v131, v99
	s_nop 1
	v_permlane16_swap_b32_e32 v131, v99
	v_lshl_add_u64 v[96:97], s[78:79], 0, v[128:129]
	v_lshl_add_u64 v[102:103], v[96:97], 0, v[160:161]
	v_cvt_pk_bf16_f32 v107, v162, v107
	global_store_dwordx4 v[108:109], v[104:107], off nt
	s_waitcnt lgkmcnt(0)
	v_add_f32_e32 v96, v99, v131
	s_nop 1
	v_mov_b32_e32 v97, v96
	s_nop 1
	v_permlane32_swap_b32_e32 v97, v96
	v_cvt_pk_bf16_f32 v98, v100, v101
	v_cvt_pk_bf16_f32 v99, v110, v111
	v_cvt_pk_bf16_f32 v100, v125, v126
	v_cvt_pk_bf16_f32 v101, v127, v130
	global_store_dwordx4 v[102:103], v[98:101], off nt
	s_and_saveexec_b64 s[2:3], s[38:39]
	s_cbranch_execz .LBB0_479
	v_lshl_add_u32 v98, v124, 4, s96
	s_waitcnt lgkmcnt(0)
	v_add_f32_e32 v96, v96, v97
	ds_write_b32 v98, v96
.LBB0_479:
	s_or_b64 exec, exec, s[2:3]
	ds_read_b32 v98, v248 offset:128
	s_waitcnt lgkmcnt(1)
	v_lshlrev_b32_e32 v97, 16, v188
	v_add_u32_e32 v96, 32, v247
	v_add_u32_e32 v100, s91, v96
	v_ashrrev_i32_e32 v101, 31, v100
	s_waitcnt lgkmcnt(0)
	v_pk_mul_f32 v[92:93], v[92:93], v[98:99] op_sel_hi:[1,0]
	v_pk_mul_f32 v[94:95], v[94:95], v[98:99] op_sel_hi:[1,0]
	v_pk_mul_f32 v[92:93], v[156:157], v[92:93]
	v_pk_mul_f32 v[94:95], v[158:159], v[94:95]
	v_add_f32_e32 v97, v92, v97
	v_and_b32_e32 v92, 0xffff0000, v188
	v_pk_mul_f32 v[90:91], v[90:91], v[98:99] op_sel_hi:[1,0]
	v_pk_mul_f32 v[88:89], v[88:89], v[98:99] op_sel_hi:[1,0]
	v_add_f32_e32 v99, v93, v92
	v_lshlrev_b32_e32 v92, 16, v189
	v_add_f32_e32 v94, v94, v92
	v_and_b32_e32 v92, 0xffff0000, v189
	v_pk_mul_f32 v[88:89], v[152:153], v[88:89]
	v_add_f32_e32 v95, v95, v92
	v_lshlrev_b32_e32 v92, 16, v190
	v_add_f32_e32 v102, v88, v92
	v_and_b32_e32 v88, 0xffff0000, v190
	v_pk_mul_f32 v[90:91], v[154:155], v[90:91]
	v_add_f32_e32 v103, v89, v88
	v_lshlrev_b32_e32 v88, 16, v191
	v_add_f32_e32 v104, v90, v88
	v_and_b32_e32 v88, 0xffff0000, v191
	v_add_f32_e32 v91, v91, v88
	v_mul_f32_e32 v88, v99, v99
	v_mul_f32_e32 v89, v95, v95
	v_fmac_f32_e32 v88, v97, v97
	v_fmac_f32_e32 v89, v94, v94
	v_add_f32_e32 v88, v88, v89
	v_mul_f32_e32 v89, v103, v103
	v_fmac_f32_e32 v89, v102, v102
	v_add_f32_e32 v88, v89, v88
	v_mul_f32_e32 v89, v91, v91
	v_lshlrev_b64 v[100:101], 6, v[100:101]
	v_fmac_f32_e32 v89, v104, v104
	v_add_f32_e32 v105, v89, v88
	v_lshl_add_u64 v[88:89], s[48:49], 0, v[100:101]
	v_pk_mul_f32 v[84:85], v[84:85], v[98:99] op_sel_hi:[1,0]
	v_lshl_add_u64 v[92:93], v[88:89], 0, v[160:161]
	v_cvt_pk_bf16_f32 v88, v97, v99
	v_cvt_pk_bf16_f32 v89, v94, v95
	v_pk_mul_f32 v[84:85], v[144:145], v[84:85]
	v_lshlrev_b32_e32 v94, 16, v184
	v_pk_mul_f32 v[86:87], v[86:87], v[98:99] op_sel_hi:[1,0]
	v_add_f32_e32 v84, v84, v94
	v_and_b32_e32 v94, 0xffff0000, v184
	v_pk_mul_f32 v[86:87], v[146:147], v[86:87]
	v_add_f32_e32 v85, v85, v94
	v_lshlrev_b32_e32 v94, 16, v185
	v_pk_mul_f32 v[80:81], v[80:81], v[98:99] op_sel_hi:[1,0]
	v_add_f32_e32 v94, v86, v94
	v_and_b32_e32 v86, 0xffff0000, v185
	v_pk_mul_f32 v[80:81], v[140:141], v[80:81]
	v_add_f32_e32 v95, v87, v86
	v_lshlrev_b32_e32 v86, 16, v186
	v_pk_mul_f32 v[82:83], v[82:83], v[98:99] op_sel_hi:[1,0]
	v_add_f32_e32 v97, v80, v86
	v_and_b32_e32 v80, 0xffff0000, v186
	v_pk_mul_f32 v[82:83], v[142:143], v[82:83]
	v_add_f32_e32 v98, v81, v80
	v_lshlrev_b32_e32 v80, 16, v187
	v_add_f32_e32 v99, v82, v80
	v_and_b32_e32 v80, 0xffff0000, v187
	v_cvt_pk_bf16_f32 v90, v102, v103
	v_add_f32_e32 v102, v83, v80
	v_mul_f32_e32 v80, v85, v85
	v_mul_f32_e32 v81, v95, v95
	v_fmac_f32_e32 v80, v84, v84
	v_fmac_f32_e32 v81, v94, v94
	v_add_f32_e32 v80, v80, v81
	v_mul_f32_e32 v81, v98, v98
	v_fmac_f32_e32 v81, v97, v97
	v_add_f32_e32 v80, v81, v80
	v_mul_f32_e32 v81, v102, v102
	v_fmac_f32_e32 v81, v99, v99
	v_add_f32_e32 v80, v81, v80
	v_add_f32_e32 v83, v105, v80
	s_nop 1
	v_mov_b32_e32 v103, v83
	s_nop 1
	v_permlane16_swap_b32_e32 v103, v83
	v_lshl_add_u64 v[80:81], s[78:79], 0, v[100:101]
	v_lshl_add_u64 v[86:87], v[80:81], 0, v[160:161]
	v_cvt_pk_bf16_f32 v91, v104, v91
	global_store_dwordx4 v[92:93], v[88:91], off nt
	s_waitcnt lgkmcnt(0)
	v_add_f32_e32 v80, v83, v103
	s_nop 1
	v_mov_b32_e32 v81, v80
	s_nop 1
	v_permlane32_swap_b32_e32 v81, v80
	v_cvt_pk_bf16_f32 v82, v84, v85
	v_cvt_pk_bf16_f32 v83, v94, v95
	v_cvt_pk_bf16_f32 v84, v97, v98
	v_cvt_pk_bf16_f32 v85, v99, v102
	global_store_dwordx4 v[86:87], v[82:85], off nt
	s_and_saveexec_b64 s[2:3], s[38:39]
	s_cbranch_execz .LBB0_481
	v_lshl_add_u32 v82, v96, 4, s96
	s_waitcnt lgkmcnt(0)
	v_add_f32_e32 v80, v80, v81
	ds_write_b32 v82, v80
.LBB0_481:
	s_or_b64 exec, exec, s[2:3]
	ds_read_b32 v82, v248 offset:192
	s_waitcnt lgkmcnt(1)
	v_lshlrev_b32_e32 v81, 16, v180
	v_add_u32_e32 v80, 48, v247
	v_add_u32_e32 v84, s91, v80
	v_ashrrev_i32_e32 v85, 31, v84
	s_waitcnt lgkmcnt(0)
	v_pk_mul_f32 v[76:77], v[76:77], v[82:83] op_sel_hi:[1,0]
	v_pk_mul_f32 v[78:79], v[78:79], v[82:83] op_sel_hi:[1,0]
	v_pk_mul_f32 v[76:77], v[156:157], v[76:77]
	v_pk_mul_f32 v[78:79], v[158:159], v[78:79]
	v_add_f32_e32 v81, v76, v81
	v_and_b32_e32 v76, 0xffff0000, v180
	v_pk_mul_f32 v[74:75], v[74:75], v[82:83] op_sel_hi:[1,0]
	v_pk_mul_f32 v[72:73], v[72:73], v[82:83] op_sel_hi:[1,0]
	v_add_f32_e32 v83, v77, v76
	v_lshlrev_b32_e32 v76, 16, v181
	v_add_f32_e32 v78, v78, v76
	v_and_b32_e32 v76, 0xffff0000, v181
	v_pk_mul_f32 v[72:73], v[152:153], v[72:73]
	v_add_f32_e32 v79, v79, v76
	v_lshlrev_b32_e32 v76, 16, v182
	v_add_f32_e32 v86, v72, v76
	v_and_b32_e32 v72, 0xffff0000, v182
	v_pk_mul_f32 v[74:75], v[154:155], v[74:75]
	v_add_f32_e32 v87, v73, v72
	v_lshlrev_b32_e32 v72, 16, v183
	v_add_f32_e32 v88, v74, v72
	v_and_b32_e32 v72, 0xffff0000, v183
	v_add_f32_e32 v75, v75, v72
	v_mul_f32_e32 v72, v83, v83
	v_mul_f32_e32 v73, v79, v79
	v_fmac_f32_e32 v72, v81, v81
	v_fmac_f32_e32 v73, v78, v78
	v_add_f32_e32 v72, v72, v73
	v_mul_f32_e32 v73, v87, v87
	v_fmac_f32_e32 v73, v86, v86
	v_add_f32_e32 v72, v73, v72
	v_mul_f32_e32 v73, v75, v75
	v_lshlrev_b64 v[84:85], 6, v[84:85]
	v_fmac_f32_e32 v73, v88, v88
	v_add_f32_e32 v89, v73, v72
	v_lshl_add_u64 v[72:73], s[48:49], 0, v[84:85]
	v_pk_mul_f32 v[68:69], v[68:69], v[82:83] op_sel_hi:[1,0]
	v_lshl_add_u64 v[76:77], v[72:73], 0, v[160:161]
	v_cvt_pk_bf16_f32 v72, v81, v83
	v_cvt_pk_bf16_f32 v73, v78, v79
	v_pk_mul_f32 v[68:69], v[144:145], v[68:69]
	v_lshlrev_b32_e32 v78, 16, v176
	v_pk_mul_f32 v[70:71], v[70:71], v[82:83] op_sel_hi:[1,0]
	v_add_f32_e32 v68, v68, v78
	v_and_b32_e32 v78, 0xffff0000, v176
	v_pk_mul_f32 v[70:71], v[146:147], v[70:71]
	v_add_f32_e32 v69, v69, v78
	v_lshlrev_b32_e32 v78, 16, v177
	v_pk_mul_f32 v[64:65], v[64:65], v[82:83] op_sel_hi:[1,0]
	v_add_f32_e32 v78, v70, v78
	v_and_b32_e32 v70, 0xffff0000, v177
	v_pk_mul_f32 v[64:65], v[140:141], v[64:65]
	v_add_f32_e32 v79, v71, v70
	v_lshlrev_b32_e32 v70, 16, v178
	v_pk_mul_f32 v[66:67], v[66:67], v[82:83] op_sel_hi:[1,0]
	v_add_f32_e32 v81, v64, v70
	v_and_b32_e32 v64, 0xffff0000, v178
	v_pk_mul_f32 v[66:67], v[142:143], v[66:67]
	v_add_f32_e32 v82, v65, v64
	v_lshlrev_b32_e32 v64, 16, v179
	v_add_f32_e32 v83, v66, v64
	v_and_b32_e32 v64, 0xffff0000, v179
	v_cvt_pk_bf16_f32 v74, v86, v87
	v_add_f32_e32 v86, v67, v64
	v_mul_f32_e32 v64, v69, v69
	v_mul_f32_e32 v65, v79, v79
	v_fmac_f32_e32 v64, v68, v68
	v_fmac_f32_e32 v65, v78, v78
	v_add_f32_e32 v64, v64, v65
	v_mul_f32_e32 v65, v82, v82
	v_fmac_f32_e32 v65, v81, v81
	v_add_f32_e32 v64, v65, v64
	v_mul_f32_e32 v65, v86, v86
	v_fmac_f32_e32 v65, v83, v83
	v_add_f32_e32 v64, v65, v64
	v_add_f32_e32 v67, v89, v64
	s_nop 1
	v_mov_b32_e32 v87, v67
	s_nop 1
	v_permlane16_swap_b32_e32 v87, v67
	v_lshl_add_u64 v[64:65], s[78:79], 0, v[84:85]
	v_lshl_add_u64 v[70:71], v[64:65], 0, v[160:161]
	v_cvt_pk_bf16_f32 v75, v88, v75
	global_store_dwordx4 v[76:77], v[72:75], off nt
	s_waitcnt lgkmcnt(0)
	v_add_f32_e32 v64, v67, v87
	s_nop 1
	v_mov_b32_e32 v65, v64
	s_nop 1
	v_permlane32_swap_b32_e32 v65, v64
	v_cvt_pk_bf16_f32 v66, v68, v69
	v_cvt_pk_bf16_f32 v67, v78, v79
	v_cvt_pk_bf16_f32 v68, v81, v82
	v_cvt_pk_bf16_f32 v69, v83, v86
	global_store_dwordx4 v[70:71], v[66:69], off nt
	s_and_saveexec_b64 s[2:3], s[38:39]
	s_cbranch_execz .LBB0_483
	v_lshl_add_u32 v66, v80, 4, s96
	s_waitcnt lgkmcnt(0)
	v_add_f32_e32 v64, v64, v65
	ds_write_b32 v66, v64
.LBB0_483:
	s_or_b64 exec, exec, s[2:3]
	ds_read_b32 v66, v248 offset:512
	s_waitcnt lgkmcnt(1)
	v_lshlrev_b32_e32 v65, 16, v172
	v_add_u32_e32 v64, 0x80, v247
	v_add_u32_e32 v68, s91, v64
	v_ashrrev_i32_e32 v69, 31, v68
	s_waitcnt lgkmcnt(0)
	v_pk_mul_f32 v[60:61], v[60:61], v[66:67] op_sel_hi:[1,0]
	v_pk_mul_f32 v[62:63], v[62:63], v[66:67] op_sel_hi:[1,0]
	v_pk_mul_f32 v[60:61], v[156:157], v[60:61]
	v_pk_mul_f32 v[62:63], v[158:159], v[62:63]
	v_add_f32_e32 v65, v60, v65
	v_and_b32_e32 v60, 0xffff0000, v172
	v_pk_mul_f32 v[58:59], v[58:59], v[66:67] op_sel_hi:[1,0]
	v_pk_mul_f32 v[56:57], v[56:57], v[66:67] op_sel_hi:[1,0]
	v_add_f32_e32 v67, v61, v60
	v_lshlrev_b32_e32 v60, 16, v173
	v_add_f32_e32 v62, v62, v60
	v_and_b32_e32 v60, 0xffff0000, v173
	v_pk_mul_f32 v[56:57], v[152:153], v[56:57]
	v_add_f32_e32 v63, v63, v60
	v_lshlrev_b32_e32 v60, 16, v174
	v_add_f32_e32 v70, v56, v60
	v_and_b32_e32 v56, 0xffff0000, v174
	v_pk_mul_f32 v[58:59], v[154:155], v[58:59]
	v_add_f32_e32 v71, v57, v56
	v_lshlrev_b32_e32 v56, 16, v175
	v_add_f32_e32 v72, v58, v56
	v_and_b32_e32 v56, 0xffff0000, v175
	v_add_f32_e32 v59, v59, v56
	v_mul_f32_e32 v56, v67, v67
	v_mul_f32_e32 v57, v63, v63
	v_fmac_f32_e32 v56, v65, v65
	v_fmac_f32_e32 v57, v62, v62
	v_add_f32_e32 v56, v56, v57
	v_mul_f32_e32 v57, v71, v71
	v_fmac_f32_e32 v57, v70, v70
	v_add_f32_e32 v56, v57, v56
	v_mul_f32_e32 v57, v59, v59
	v_lshlrev_b64 v[68:69], 6, v[68:69]
	v_fmac_f32_e32 v57, v72, v72
	v_add_f32_e32 v73, v57, v56
	v_lshl_add_u64 v[56:57], s[48:49], 0, v[68:69]
	v_pk_mul_f32 v[52:53], v[52:53], v[66:67] op_sel_hi:[1,0]
	v_lshl_add_u64 v[60:61], v[56:57], 0, v[160:161]
	v_cvt_pk_bf16_f32 v56, v65, v67
	v_cvt_pk_bf16_f32 v57, v62, v63
	v_pk_mul_f32 v[52:53], v[144:145], v[52:53]
	v_lshlrev_b32_e32 v62, 16, v168
	v_pk_mul_f32 v[54:55], v[54:55], v[66:67] op_sel_hi:[1,0]
	v_add_f32_e32 v52, v52, v62
	v_and_b32_e32 v62, 0xffff0000, v168
	v_pk_mul_f32 v[54:55], v[146:147], v[54:55]
	v_add_f32_e32 v53, v53, v62
	v_lshlrev_b32_e32 v62, 16, v169
	v_pk_mul_f32 v[48:49], v[48:49], v[66:67] op_sel_hi:[1,0]
	v_add_f32_e32 v62, v54, v62
	v_and_b32_e32 v54, 0xffff0000, v169
	v_pk_mul_f32 v[48:49], v[140:141], v[48:49]
	v_add_f32_e32 v63, v55, v54
	v_lshlrev_b32_e32 v54, 16, v170
	v_pk_mul_f32 v[50:51], v[50:51], v[66:67] op_sel_hi:[1,0]
	v_add_f32_e32 v65, v48, v54
	v_and_b32_e32 v48, 0xffff0000, v170
	v_pk_mul_f32 v[50:51], v[142:143], v[50:51]
	v_add_f32_e32 v66, v49, v48
	v_lshlrev_b32_e32 v48, 16, v171
	v_add_f32_e32 v67, v50, v48
	v_and_b32_e32 v48, 0xffff0000, v171
	v_cvt_pk_bf16_f32 v58, v70, v71
	v_add_f32_e32 v70, v51, v48
	v_mul_f32_e32 v48, v53, v53
	v_mul_f32_e32 v49, v63, v63
	v_fmac_f32_e32 v48, v52, v52
	v_fmac_f32_e32 v49, v62, v62
	v_add_f32_e32 v48, v48, v49
	v_mul_f32_e32 v49, v66, v66
	v_fmac_f32_e32 v49, v65, v65
	v_add_f32_e32 v48, v49, v48
	v_mul_f32_e32 v49, v70, v70
	v_fmac_f32_e32 v49, v67, v67
	v_add_f32_e32 v48, v49, v48
	v_add_f32_e32 v51, v73, v48
	s_nop 1
	v_mov_b32_e32 v71, v51
	s_nop 1
	v_permlane16_swap_b32_e32 v71, v51
	v_lshl_add_u64 v[48:49], s[78:79], 0, v[68:69]
	v_lshl_add_u64 v[54:55], v[48:49], 0, v[160:161]
	v_cvt_pk_bf16_f32 v59, v72, v59
	global_store_dwordx4 v[60:61], v[56:59], off nt
	s_waitcnt lgkmcnt(0)
	v_add_f32_e32 v48, v51, v71
	s_nop 1
	v_mov_b32_e32 v49, v48
	s_nop 1
	v_permlane32_swap_b32_e32 v49, v48
	v_cvt_pk_bf16_f32 v50, v52, v53
	v_cvt_pk_bf16_f32 v51, v62, v63
	v_cvt_pk_bf16_f32 v52, v65, v66
	v_cvt_pk_bf16_f32 v53, v67, v70
	global_store_dwordx4 v[54:55], v[50:53], off nt
	s_and_saveexec_b64 s[2:3], s[38:39]
	s_cbranch_execz .LBB0_485
	v_lshl_add_u32 v50, v64, 4, s96
	s_waitcnt lgkmcnt(0)
	v_add_f32_e32 v48, v48, v49
	ds_write_b32 v50, v48
.LBB0_485:
	s_or_b64 exec, exec, s[2:3]
	ds_read_b32 v50, v248 offset:576
	s_waitcnt lgkmcnt(1)
	v_lshlrev_b32_e32 v49, 16, v148
	v_add_u32_e32 v48, 0x90, v247
	v_add_u32_e32 v52, s91, v48
	v_ashrrev_i32_e32 v53, 31, v52
	s_waitcnt lgkmcnt(0)
	v_pk_mul_f32 v[44:45], v[44:45], v[50:51] op_sel_hi:[1,0]
	v_pk_mul_f32 v[46:47], v[46:47], v[50:51] op_sel_hi:[1,0]
	v_pk_mul_f32 v[44:45], v[156:157], v[44:45]
	v_pk_mul_f32 v[46:47], v[158:159], v[46:47]
	v_add_f32_e32 v49, v44, v49
	v_and_b32_e32 v44, 0xffff0000, v148
	v_pk_mul_f32 v[42:43], v[42:43], v[50:51] op_sel_hi:[1,0]
	v_pk_mul_f32 v[40:41], v[40:41], v[50:51] op_sel_hi:[1,0]
	v_add_f32_e32 v51, v45, v44
	v_lshlrev_b32_e32 v44, 16, v149
	v_add_f32_e32 v46, v46, v44
	v_and_b32_e32 v44, 0xffff0000, v149
	v_pk_mul_f32 v[40:41], v[152:153], v[40:41]
	v_add_f32_e32 v47, v47, v44
	v_lshlrev_b32_e32 v44, 16, v150
	v_add_f32_e32 v54, v40, v44
	v_and_b32_e32 v40, 0xffff0000, v150
	v_pk_mul_f32 v[42:43], v[154:155], v[42:43]
	v_add_f32_e32 v55, v41, v40
	v_lshlrev_b32_e32 v40, 16, v151
	v_add_f32_e32 v56, v42, v40
	v_and_b32_e32 v40, 0xffff0000, v151
	v_add_f32_e32 v43, v43, v40
	v_mul_f32_e32 v40, v51, v51
	v_mul_f32_e32 v41, v47, v47
	v_fmac_f32_e32 v40, v49, v49
	v_fmac_f32_e32 v41, v46, v46
	v_add_f32_e32 v40, v40, v41
	v_mul_f32_e32 v41, v55, v55
	v_fmac_f32_e32 v41, v54, v54
	v_add_f32_e32 v40, v41, v40
	v_mul_f32_e32 v41, v43, v43
	v_lshlrev_b64 v[52:53], 6, v[52:53]
	v_fmac_f32_e32 v41, v56, v56
	v_add_f32_e32 v57, v41, v40
	v_lshl_add_u64 v[40:41], s[48:49], 0, v[52:53]
	v_pk_mul_f32 v[36:37], v[36:37], v[50:51] op_sel_hi:[1,0]
	v_lshl_add_u64 v[44:45], v[40:41], 0, v[160:161]
	v_cvt_pk_bf16_f32 v40, v49, v51
	v_cvt_pk_bf16_f32 v41, v46, v47
	v_pk_mul_f32 v[36:37], v[144:145], v[36:37]
	v_lshlrev_b32_e32 v46, 16, v136
	v_pk_mul_f32 v[38:39], v[38:39], v[50:51] op_sel_hi:[1,0]
	v_add_f32_e32 v36, v36, v46
	v_and_b32_e32 v46, 0xffff0000, v136
	v_pk_mul_f32 v[38:39], v[146:147], v[38:39]
	v_add_f32_e32 v37, v37, v46
	v_lshlrev_b32_e32 v46, 16, v137
	v_pk_mul_f32 v[32:33], v[32:33], v[50:51] op_sel_hi:[1,0]
	v_add_f32_e32 v46, v38, v46
	v_and_b32_e32 v38, 0xffff0000, v137
	v_pk_mul_f32 v[32:33], v[140:141], v[32:33]
	v_add_f32_e32 v47, v39, v38
	v_lshlrev_b32_e32 v38, 16, v138
	v_pk_mul_f32 v[34:35], v[34:35], v[50:51] op_sel_hi:[1,0]
	v_add_f32_e32 v49, v32, v38
	v_and_b32_e32 v32, 0xffff0000, v138
	v_pk_mul_f32 v[34:35], v[142:143], v[34:35]
	v_add_f32_e32 v50, v33, v32
	v_lshlrev_b32_e32 v32, 16, v139
	v_add_f32_e32 v51, v34, v32
	v_and_b32_e32 v32, 0xffff0000, v139
	v_cvt_pk_bf16_f32 v42, v54, v55
	v_add_f32_e32 v54, v35, v32
	v_mul_f32_e32 v32, v37, v37
	v_mul_f32_e32 v33, v47, v47
	v_fmac_f32_e32 v32, v36, v36
	v_fmac_f32_e32 v33, v46, v46
	v_add_f32_e32 v32, v32, v33
	v_mul_f32_e32 v33, v50, v50
	v_fmac_f32_e32 v33, v49, v49
	v_add_f32_e32 v32, v33, v32
	v_mul_f32_e32 v33, v54, v54
	v_fmac_f32_e32 v33, v51, v51
	v_add_f32_e32 v32, v33, v32
	v_add_f32_e32 v35, v57, v32
	s_nop 1
	v_mov_b32_e32 v55, v35
	s_nop 1
	v_permlane16_swap_b32_e32 v55, v35
	v_lshl_add_u64 v[32:33], s[78:79], 0, v[52:53]
	v_lshl_add_u64 v[38:39], v[32:33], 0, v[160:161]
	v_cvt_pk_bf16_f32 v43, v56, v43
	global_store_dwordx4 v[44:45], v[40:43], off nt
	s_waitcnt lgkmcnt(0)
	v_add_f32_e32 v32, v35, v55
	s_nop 1
	v_mov_b32_e32 v33, v32
	s_nop 1
	v_permlane32_swap_b32_e32 v33, v32
	v_cvt_pk_bf16_f32 v34, v36, v37
	v_cvt_pk_bf16_f32 v35, v46, v47
	v_cvt_pk_bf16_f32 v36, v49, v50
	v_cvt_pk_bf16_f32 v37, v51, v54
	global_store_dwordx4 v[38:39], v[34:37], off nt
	s_and_saveexec_b64 s[2:3], s[38:39]
	s_cbranch_execz .LBB0_487
	v_lshl_add_u32 v34, v48, 4, s96
	s_waitcnt lgkmcnt(0)
	v_add_f32_e32 v32, v32, v33
	ds_write_b32 v34, v32
.LBB0_487:
	s_or_b64 exec, exec, s[2:3]
	ds_read_b32 v34, v248 offset:640
	s_waitcnt lgkmcnt(1)
	v_lshlrev_b32_e32 v33, 16, v132
	v_add_u32_e32 v32, 0xa0, v247
	v_add_u32_e32 v36, s91, v32
	v_ashrrev_i32_e32 v37, 31, v36
	s_waitcnt lgkmcnt(0)
	v_pk_mul_f32 v[28:29], v[28:29], v[34:35] op_sel_hi:[1,0]
	v_pk_mul_f32 v[30:31], v[30:31], v[34:35] op_sel_hi:[1,0]
	v_pk_mul_f32 v[28:29], v[156:157], v[28:29]
	v_pk_mul_f32 v[30:31], v[158:159], v[30:31]
	v_add_f32_e32 v33, v28, v33
	v_and_b32_e32 v28, 0xffff0000, v132
	v_pk_mul_f32 v[26:27], v[26:27], v[34:35] op_sel_hi:[1,0]
	v_pk_mul_f32 v[24:25], v[24:25], v[34:35] op_sel_hi:[1,0]
	v_add_f32_e32 v35, v29, v28
	v_lshlrev_b32_e32 v28, 16, v133
	v_add_f32_e32 v30, v30, v28
	v_and_b32_e32 v28, 0xffff0000, v133
	v_pk_mul_f32 v[24:25], v[152:153], v[24:25]
	v_add_f32_e32 v31, v31, v28
	v_lshlrev_b32_e32 v28, 16, v134
	v_add_f32_e32 v38, v24, v28
	v_and_b32_e32 v24, 0xffff0000, v134
	v_pk_mul_f32 v[26:27], v[154:155], v[26:27]
	v_add_f32_e32 v39, v25, v24
	v_lshlrev_b32_e32 v24, 16, v135
	v_add_f32_e32 v40, v26, v24
	v_and_b32_e32 v24, 0xffff0000, v135
	v_add_f32_e32 v27, v27, v24
	v_mul_f32_e32 v24, v35, v35
	v_mul_f32_e32 v25, v31, v31
	v_fmac_f32_e32 v24, v33, v33
	v_fmac_f32_e32 v25, v30, v30
	v_add_f32_e32 v24, v24, v25
	v_mul_f32_e32 v25, v39, v39
	v_fmac_f32_e32 v25, v38, v38
	v_add_f32_e32 v24, v25, v24
	v_mul_f32_e32 v25, v27, v27
	v_lshlrev_b64 v[36:37], 6, v[36:37]
	v_fmac_f32_e32 v25, v40, v40
	v_add_f32_e32 v41, v25, v24
	v_lshl_add_u64 v[24:25], s[48:49], 0, v[36:37]
	v_pk_mul_f32 v[20:21], v[20:21], v[34:35] op_sel_hi:[1,0]
	v_lshl_add_u64 v[28:29], v[24:25], 0, v[160:161]
	v_cvt_pk_bf16_f32 v24, v33, v35
	v_cvt_pk_bf16_f32 v25, v30, v31
	v_pk_mul_f32 v[20:21], v[144:145], v[20:21]
	v_lshlrev_b32_e32 v30, 16, v120
	v_pk_mul_f32 v[22:23], v[22:23], v[34:35] op_sel_hi:[1,0]
	v_add_f32_e32 v20, v20, v30
	v_and_b32_e32 v30, 0xffff0000, v120
	v_pk_mul_f32 v[22:23], v[146:147], v[22:23]
	v_add_f32_e32 v21, v21, v30
	v_lshlrev_b32_e32 v30, 16, v121
	v_pk_mul_f32 v[16:17], v[16:17], v[34:35] op_sel_hi:[1,0]
	v_add_f32_e32 v30, v22, v30
	v_and_b32_e32 v22, 0xffff0000, v121
	v_pk_mul_f32 v[16:17], v[140:141], v[16:17]
	v_add_f32_e32 v31, v23, v22
	v_lshlrev_b32_e32 v22, 16, v122
	v_pk_mul_f32 v[18:19], v[18:19], v[34:35] op_sel_hi:[1,0]
	v_add_f32_e32 v33, v16, v22
	v_and_b32_e32 v16, 0xffff0000, v122
	v_pk_mul_f32 v[18:19], v[142:143], v[18:19]
	v_add_f32_e32 v34, v17, v16
	v_lshlrev_b32_e32 v16, 16, v123
	v_add_f32_e32 v35, v18, v16
	v_and_b32_e32 v16, 0xffff0000, v123
	v_cvt_pk_bf16_f32 v26, v38, v39
	v_add_f32_e32 v38, v19, v16
	v_mul_f32_e32 v16, v21, v21
	v_mul_f32_e32 v17, v31, v31
	v_fmac_f32_e32 v16, v20, v20
	v_fmac_f32_e32 v17, v30, v30
	v_add_f32_e32 v16, v16, v17
	v_mul_f32_e32 v17, v34, v34
	v_fmac_f32_e32 v17, v33, v33
	v_add_f32_e32 v16, v17, v16
	v_mul_f32_e32 v17, v38, v38
	v_fmac_f32_e32 v17, v35, v35
	v_add_f32_e32 v16, v17, v16
	v_add_f32_e32 v19, v41, v16
	s_nop 1
	v_mov_b32_e32 v39, v19
	s_nop 1
	v_permlane16_swap_b32_e32 v39, v19
	v_lshl_add_u64 v[16:17], s[78:79], 0, v[36:37]
	v_lshl_add_u64 v[22:23], v[16:17], 0, v[160:161]
	v_cvt_pk_bf16_f32 v27, v40, v27
	global_store_dwordx4 v[28:29], v[24:27], off nt
	s_waitcnt lgkmcnt(0)
	v_add_f32_e32 v16, v19, v39
	s_nop 1
	v_mov_b32_e32 v17, v16
	s_nop 1
	v_permlane32_swap_b32_e32 v17, v16
	v_cvt_pk_bf16_f32 v18, v20, v21
	v_cvt_pk_bf16_f32 v19, v30, v31
	v_cvt_pk_bf16_f32 v20, v33, v34
	v_cvt_pk_bf16_f32 v21, v35, v38
	global_store_dwordx4 v[22:23], v[18:21], off nt
	s_and_saveexec_b64 s[2:3], s[38:39]
	s_cbranch_execz .LBB0_489
	v_lshl_add_u32 v18, v32, 4, s96
	s_waitcnt lgkmcnt(0)
	v_add_f32_e32 v16, v16, v17
	ds_write_b32 v18, v16
.LBB0_489:
	s_or_b64 exec, exec, s[2:3]
	ds_read_b32 v18, v248 offset:704
	s_waitcnt lgkmcnt(1)
	v_lshlrev_b32_e32 v17, 16, v116
	v_add_u32_e32 v16, 0xb0, v247
	v_add_u32_e32 v20, s91, v16
	v_ashrrev_i32_e32 v21, 31, v20
	s_waitcnt lgkmcnt(0)
	v_pk_mul_f32 v[12:13], v[12:13], v[18:19] op_sel_hi:[1,0]
	v_pk_mul_f32 v[14:15], v[14:15], v[18:19] op_sel_hi:[1,0]
	v_pk_mul_f32 v[12:13], v[156:157], v[12:13]
	v_pk_mul_f32 v[14:15], v[158:159], v[14:15]
	v_add_f32_e32 v17, v12, v17
	v_and_b32_e32 v12, 0xffff0000, v116
	v_pk_mul_f32 v[10:11], v[10:11], v[18:19] op_sel_hi:[1,0]
	v_pk_mul_f32 v[8:9], v[8:9], v[18:19] op_sel_hi:[1,0]
	v_add_f32_e32 v19, v13, v12
	v_lshlrev_b32_e32 v12, 16, v117
	v_add_f32_e32 v14, v14, v12
	v_and_b32_e32 v12, 0xffff0000, v117
	v_pk_mul_f32 v[8:9], v[152:153], v[8:9]
	v_add_f32_e32 v15, v15, v12
	v_lshlrev_b32_e32 v12, 16, v118
	v_add_f32_e32 v22, v8, v12
	v_and_b32_e32 v8, 0xffff0000, v118
	v_pk_mul_f32 v[10:11], v[154:155], v[10:11]
	v_add_f32_e32 v23, v9, v8
	v_lshlrev_b32_e32 v8, 16, v119
	v_add_f32_e32 v24, v10, v8
	v_and_b32_e32 v8, 0xffff0000, v119
	v_add_f32_e32 v11, v11, v8
	v_mul_f32_e32 v8, v19, v19
	v_mul_f32_e32 v9, v15, v15
	v_fmac_f32_e32 v8, v17, v17
	v_fmac_f32_e32 v9, v14, v14
	v_add_f32_e32 v8, v8, v9
	v_mul_f32_e32 v9, v23, v23
	v_fmac_f32_e32 v9, v22, v22
	v_add_f32_e32 v8, v9, v8
	v_mul_f32_e32 v9, v11, v11
	v_lshlrev_b64 v[20:21], 6, v[20:21]
	v_fmac_f32_e32 v9, v24, v24
	v_add_f32_e32 v25, v9, v8
	v_lshl_add_u64 v[8:9], s[48:49], 0, v[20:21]
	v_pk_mul_f32 v[4:5], v[4:5], v[18:19] op_sel_hi:[1,0]
	v_lshl_add_u64 v[12:13], v[8:9], 0, v[160:161]
	v_cvt_pk_bf16_f32 v8, v17, v19
	v_cvt_pk_bf16_f32 v9, v14, v15
	v_pk_mul_f32 v[4:5], v[144:145], v[4:5]
	v_lshlrev_b32_e32 v14, 16, v112
	v_pk_mul_f32 v[6:7], v[6:7], v[18:19] op_sel_hi:[1,0]
	v_add_f32_e32 v4, v4, v14
	v_and_b32_e32 v14, 0xffff0000, v112
	v_pk_mul_f32 v[6:7], v[146:147], v[6:7]
	v_add_f32_e32 v5, v5, v14
	v_lshlrev_b32_e32 v14, 16, v113
	v_pk_mul_f32 v[0:1], v[0:1], v[18:19] op_sel_hi:[1,0]
	v_add_f32_e32 v14, v6, v14
	v_and_b32_e32 v6, 0xffff0000, v113
	v_pk_mul_f32 v[0:1], v[140:141], v[0:1]
	v_add_f32_e32 v15, v7, v6
	v_lshlrev_b32_e32 v6, 16, v114
	v_pk_mul_f32 v[2:3], v[2:3], v[18:19] op_sel_hi:[1,0]
	v_add_f32_e32 v17, v0, v6
	v_and_b32_e32 v0, 0xffff0000, v114
	v_pk_mul_f32 v[2:3], v[142:143], v[2:3]
	v_add_f32_e32 v18, v1, v0
	v_lshlrev_b32_e32 v0, 16, v115
	v_add_f32_e32 v19, v2, v0
	v_and_b32_e32 v0, 0xffff0000, v115
	v_cvt_pk_bf16_f32 v10, v22, v23
	v_add_f32_e32 v22, v3, v0
	v_mul_f32_e32 v0, v5, v5
	v_mul_f32_e32 v1, v15, v15
	v_fmac_f32_e32 v0, v4, v4
	v_fmac_f32_e32 v1, v14, v14
	v_add_f32_e32 v0, v0, v1
	v_mul_f32_e32 v1, v18, v18
	v_fmac_f32_e32 v1, v17, v17
	v_add_f32_e32 v0, v1, v0
	v_mul_f32_e32 v1, v22, v22
	v_fmac_f32_e32 v1, v19, v19
	v_add_f32_e32 v0, v1, v0
	v_add_f32_e32 v3, v25, v0
	s_nop 1
	v_mov_b32_e32 v23, v3
	s_nop 1
	v_permlane16_swap_b32_e32 v23, v3
	v_lshl_add_u64 v[0:1], s[78:79], 0, v[20:21]
	v_lshl_add_u64 v[6:7], v[0:1], 0, v[160:161]
	v_cvt_pk_bf16_f32 v11, v24, v11
	global_store_dwordx4 v[12:13], v[8:11], off nt
	s_waitcnt lgkmcnt(0)
	v_add_f32_e32 v0, v3, v23
	s_nop 1
	v_mov_b32_e32 v1, v0
	s_nop 1
	v_permlane32_swap_b32_e32 v1, v0
	v_cvt_pk_bf16_f32 v2, v4, v5
	v_cvt_pk_bf16_f32 v3, v14, v15
	v_cvt_pk_bf16_f32 v4, v17, v18
	v_cvt_pk_bf16_f32 v5, v19, v22
	global_store_dwordx4 v[6:7], v[2:5], off nt
	s_and_saveexec_b64 s[2:3], s[38:39]
	s_cbranch_execz .LBB0_491
	v_lshl_add_u32 v2, v16, 4, s96
	s_waitcnt lgkmcnt(0)
	v_add_f32_e32 v0, v0, v1
	ds_write_b32 v2, v0

.LBB0_657:
	v_and_b32_e32 v89, 64, v245
	v_xor_b32_e32 v88, 16, v245
	v_add_u32_e32 v89, 64, v89
	v_cmp_lt_i32_e32 vcc, v88, v89
	v_mul_f32_e32 v90, v167, v167
	v_fmac_f32_e32 v90, v166, v166
	v_cndmask_b32_e32 v88, v245, v88, vcc
	v_lshlrev_b32_e32 v250, 2, v88
	v_mul_f32_e32 v88, v165, v165
	v_fmac_f32_e32 v88, v164, v164
	v_add_f32_e32 v88, v88, v90
	v_mul_f32_e32 v90, v161, v161
	v_mul_f32_e32 v91, v163, v163
	v_fmac_f32_e32 v90, v160, v160
	v_fmac_f32_e32 v91, v162, v162
	v_add_f32_e32 v90, v90, v91
	v_add_f32_e32 v88, v88, v90
	v_mul_f32_e32 v90, v149, v149
	v_mul_f32_e32 v91, v151, v151
	v_fmac_f32_e32 v90, v148, v148
	v_fmac_f32_e32 v91, v150, v150
	v_add_f32_e32 v90, v90, v91
	v_add_f32_e32 v88, v88, v90
	v_mul_f32_e32 v90, v141, v141
	v_mul_f32_e32 v91, v143, v143
	v_fmac_f32_e32 v90, v140, v140
	v_fmac_f32_e32 v91, v142, v142
	v_add_f32_e32 v90, v90, v91
	v_add_f32_e32 v88, v88, v90
	s_nop 1
	v_mov_b32_e32 v90, v88
	s_nop 1
	v_permlane16_swap_b32_e32 v90, v88
	v_xor_b32_e32 v91, 32, v245
	v_cmp_lt_i32_e32 vcc, v91, v89
	v_mov_b32_e32 v236, v247
	s_waitcnt lgkmcnt(0)
	v_add_f32_e32 v90, v88, v90
	v_cndmask_b32_e32 v89, v245, v91, vcc
	v_lshlrev_b32_e32 v251, 2, v89
	s_nop 1
	v_mov_b32_e32 v91, v90
	s_nop 1
	v_permlane32_swap_b32_e32 v91, v90
	v_mov_b32_e32 v88, v246
	s_nop 0
	v_cmp_eq_u32_e64 s[38:39], 0, v88
	v_lshl_add_u32 v89, v236, 4, s91
	s_and_saveexec_b64 s[2:3], s[38:39]
	s_cbranch_execz .LBB0_659
	s_waitcnt lgkmcnt(0)
	v_add_f32_e32 v90, v90, v91
	ds_write_b32 v89, v90
.LBB0_659:
	s_or_b64 exec, exec, s[2:3]
	v_mul_f32_e32 v90, v121, v121
	s_waitcnt lgkmcnt(0)
	v_mul_f32_e32 v91, v123, v123
	v_fmac_f32_e32 v90, v120, v120
	v_fmac_f32_e32 v91, v122, v122
	v_add_f32_e32 v90, v90, v91
	v_mul_f32_e32 v91, v117, v117
	v_mul_f32_e32 v100, v119, v119
	v_fmac_f32_e32 v91, v116, v116
	v_fmac_f32_e32 v100, v118, v118
	v_add_f32_e32 v91, v91, v100
	v_add_f32_e32 v90, v90, v91
	v_mul_f32_e32 v91, v109, v109
	v_mul_f32_e32 v100, v111, v111
	v_fmac_f32_e32 v91, v108, v108
	v_fmac_f32_e32 v100, v110, v110
	v_add_f32_e32 v91, v91, v100
	v_add_f32_e32 v90, v90, v91
	v_mul_f32_e32 v91, v105, v105
	v_mul_f32_e32 v100, v107, v107
	v_fmac_f32_e32 v91, v104, v104
	v_fmac_f32_e32 v100, v106, v106
	v_add_f32_e32 v91, v91, v100
	v_add_f32_e32 v90, v90, v91
	s_nop 1
	v_mov_b32_e32 v91, v90
	s_nop 1
	v_permlane16_swap_b32_e32 v91, v90
	s_waitcnt lgkmcnt(0)
	v_add_f32_e32 v90, v90, v91
	s_nop 1
	v_mov_b32_e32 v91, v90
	s_nop 1
	v_permlane32_swap_b32_e32 v91, v90
	s_and_saveexec_b64 s[2:3], s[38:39]
	s_cbranch_execz .LBB0_661
	s_waitcnt lgkmcnt(0)
	v_add_f32_e32 v90, v90, v91
	ds_write_b32 v89, v90 offset:256
.LBB0_661:
	s_or_b64 exec, exec, s[2:3]
	v_mul_f32_e32 v90, v97, v97
	s_waitcnt lgkmcnt(0)
	v_mul_f32_e32 v91, v99, v99
	v_fmac_f32_e32 v90, v96, v96
	v_fmac_f32_e32 v91, v98, v98
	v_add_f32_e32 v90, v90, v91
	v_mul_f32_e32 v91, v93, v93
	v_mul_f32_e32 v100, v95, v95
	v_fmac_f32_e32 v91, v92, v92
	v_fmac_f32_e32 v100, v94, v94
	v_add_f32_e32 v91, v91, v100
	v_add_f32_e32 v90, v90, v91
	v_mul_f32_e32 v91, v85, v85
	v_mul_f32_e32 v100, v87, v87
	v_fmac_f32_e32 v91, v84, v84
	v_fmac_f32_e32 v100, v86, v86
	v_add_f32_e32 v91, v91, v100
	v_add_f32_e32 v90, v90, v91
	v_mul_f32_e32 v91, v81, v81
	v_mul_f32_e32 v100, v83, v83
	v_fmac_f32_e32 v91, v80, v80
	v_fmac_f32_e32 v100, v82, v82
	v_add_f32_e32 v91, v91, v100
	v_add_f32_e32 v90, v90, v91
	s_nop 1
	v_mov_b32_e32 v91, v90
	s_nop 1
	v_permlane16_swap_b32_e32 v91, v90
	s_waitcnt lgkmcnt(0)
	v_add_f32_e32 v90, v90, v91
	s_nop 1
	v_mov_b32_e32 v91, v90
	s_nop 1
	v_permlane32_swap_b32_e32 v91, v90
	s_and_saveexec_b64 s[2:3], s[38:39]
	s_cbranch_execz .LBB0_663
	s_waitcnt lgkmcnt(0)
	v_add_f32_e32 v90, v90, v91
	ds_write_b32 v89, v90 offset:512
.LBB0_663:
	s_or_b64 exec, exec, s[2:3]
	v_mul_f32_e32 v90, v77, v77
	s_waitcnt lgkmcnt(0)
	v_mul_f32_e32 v91, v79, v79
	v_fmac_f32_e32 v90, v76, v76
	v_fmac_f32_e32 v91, v78, v78
	v_add_f32_e32 v90, v90, v91
	v_mul_f32_e32 v91, v73, v73
	v_mul_f32_e32 v100, v75, v75
	v_fmac_f32_e32 v91, v72, v72
	v_fmac_f32_e32 v100, v74, v74
	v_add_f32_e32 v91, v91, v100
	v_add_f32_e32 v90, v90, v91
	v_mul_f32_e32 v91, v69, v69
	v_mul_f32_e32 v100, v71, v71
	v_fmac_f32_e32 v91, v68, v68
	v_fmac_f32_e32 v100, v70, v70
	v_add_f32_e32 v91, v91, v100
	v_add_f32_e32 v90, v90, v91
	v_mul_f32_e32 v91, v65, v65
	v_mul_f32_e32 v100, v67, v67
	v_fmac_f32_e32 v91, v64, v64
	v_fmac_f32_e32 v100, v66, v66
	v_add_f32_e32 v91, v91, v100
	v_add_f32_e32 v90, v90, v91
	s_nop 1
	v_mov_b32_e32 v91, v90
	s_nop 1
	v_permlane16_swap_b32_e32 v91, v90
	s_waitcnt lgkmcnt(0)
	v_add_f32_e32 v90, v90, v91
	s_nop 1
	v_mov_b32_e32 v91, v90
	s_nop 1
	v_permlane32_swap_b32_e32 v91, v90
	s_and_saveexec_b64 s[2:3], s[38:39]
	s_cbranch_execz .LBB0_665
	s_waitcnt lgkmcnt(0)
	v_add_f32_e32 v90, v90, v91
	ds_write_b32 v89, v90 offset:768
.LBB0_665:
	s_or_b64 exec, exec, s[2:3]
	v_mul_f32_e32 v90, v61, v61
	s_waitcnt lgkmcnt(0)
	v_mul_f32_e32 v91, v63, v63
	v_fmac_f32_e32 v90, v60, v60
	v_fmac_f32_e32 v91, v62, v62
	v_add_f32_e32 v90, v90, v91
	v_mul_f32_e32 v91, v57, v57
	v_mul_f32_e32 v100, v59, v59
	v_fmac_f32_e32 v91, v56, v56
	v_fmac_f32_e32 v100, v58, v58
	v_add_f32_e32 v91, v91, v100
	v_add_f32_e32 v90, v90, v91
	v_mul_f32_e32 v91, v53, v53
	v_mul_f32_e32 v100, v55, v55
	v_fmac_f32_e32 v91, v52, v52
	v_fmac_f32_e32 v100, v54, v54
	v_add_f32_e32 v91, v91, v100
	v_add_f32_e32 v90, v90, v91
	v_mul_f32_e32 v91, v49, v49
	v_mul_f32_e32 v100, v51, v51
	v_fmac_f32_e32 v91, v48, v48
	v_fmac_f32_e32 v100, v50, v50
	v_add_f32_e32 v91, v91, v100
	v_add_f32_e32 v90, v90, v91
	s_nop 1
	v_mov_b32_e32 v91, v90
	s_nop 1
	v_permlane16_swap_b32_e32 v91, v90
	s_waitcnt lgkmcnt(0)
	v_add_f32_e32 v90, v90, v91
	s_nop 1
	v_mov_b32_e32 v91, v90
	s_nop 1
	v_permlane32_swap_b32_e32 v91, v90
	s_and_saveexec_b64 s[2:3], s[38:39]
	s_cbranch_execz .LBB0_667
	s_waitcnt lgkmcnt(0)
	v_add_f32_e32 v90, v90, v91
	ds_write_b32 v89, v90 offset:2048
.LBB0_667:
	s_or_b64 exec, exec, s[2:3]
	v_mul_f32_e32 v90, v45, v45
	s_waitcnt lgkmcnt(0)
	v_mul_f32_e32 v91, v47, v47
	v_fmac_f32_e32 v90, v44, v44
	v_fmac_f32_e32 v91, v46, v46
	v_add_f32_e32 v90, v90, v91
	v_mul_f32_e32 v91, v41, v41
	v_mul_f32_e32 v100, v43, v43
	v_fmac_f32_e32 v91, v40, v40
	v_fmac_f32_e32 v100, v42, v42
	v_add_f32_e32 v91, v91, v100
	v_add_f32_e32 v90, v90, v91
	v_mul_f32_e32 v91, v37, v37
	v_mul_f32_e32 v100, v39, v39
	v_fmac_f32_e32 v91, v36, v36
	v_fmac_f32_e32 v100, v38, v38
	v_add_f32_e32 v91, v91, v100
	v_add_f32_e32 v90, v90, v91
	v_mul_f32_e32 v91, v33, v33
	v_mul_f32_e32 v100, v35, v35
	v_fmac_f32_e32 v91, v32, v32
	v_fmac_f32_e32 v100, v34, v34
	v_add_f32_e32 v91, v91, v100
	v_add_f32_e32 v90, v90, v91
	s_nop 1
	v_mov_b32_e32 v91, v90
	s_nop 1
	v_permlane16_swap_b32_e32 v91, v90
	s_waitcnt lgkmcnt(0)
	v_add_f32_e32 v90, v90, v91
	s_nop 1
	v_mov_b32_e32 v91, v90
	s_nop 1
	v_permlane32_swap_b32_e32 v91, v90
	s_and_saveexec_b64 s[2:3], s[38:39]
	s_cbranch_execz .LBB0_669
	s_waitcnt lgkmcnt(0)
	v_add_f32_e32 v90, v90, v91
	ds_write_b32 v89, v90 offset:2304
.LBB0_669:
	s_or_b64 exec, exec, s[2:3]
	v_mul_f32_e32 v90, v29, v29
	s_waitcnt lgkmcnt(0)
	v_mul_f32_e32 v91, v31, v31
	v_fmac_f32_e32 v90, v28, v28
	v_fmac_f32_e32 v91, v30, v30
	v_add_f32_e32 v90, v90, v91
	v_mul_f32_e32 v91, v25, v25
	v_mul_f32_e32 v100, v27, v27
	v_fmac_f32_e32 v91, v24, v24
	v_fmac_f32_e32 v100, v26, v26
	v_add_f32_e32 v91, v91, v100
	v_add_f32_e32 v90, v90, v91
	v_mul_f32_e32 v91, v21, v21
	v_mul_f32_e32 v100, v23, v23
	v_fmac_f32_e32 v91, v20, v20
	v_fmac_f32_e32 v100, v22, v22
	v_add_f32_e32 v91, v91, v100
	v_add_f32_e32 v90, v90, v91
	v_mul_f32_e32 v91, v17, v17
	v_mul_f32_e32 v100, v19, v19
	v_fmac_f32_e32 v91, v16, v16
	v_fmac_f32_e32 v100, v18, v18
	v_add_f32_e32 v91, v91, v100
	v_add_f32_e32 v90, v90, v91
	s_nop 1
	v_mov_b32_e32 v91, v90
	s_nop 1
	v_permlane16_swap_b32_e32 v91, v90
	s_waitcnt lgkmcnt(0)
	v_add_f32_e32 v90, v90, v91
	s_nop 1
	v_mov_b32_e32 v91, v90
	s_nop 1
	v_permlane32_swap_b32_e32 v91, v90
	s_and_saveexec_b64 s[2:3], s[38:39]
	s_cbranch_execz .LBB0_671
	s_waitcnt lgkmcnt(0)
	v_add_f32_e32 v90, v90, v91
	ds_write_b32 v89, v90 offset:2560
.LBB0_671:
	s_or_b64 exec, exec, s[2:3]
	v_mul_f32_e32 v90, v13, v13
	s_waitcnt lgkmcnt(0)
	v_mul_f32_e32 v91, v15, v15
	v_fmac_f32_e32 v90, v12, v12
	v_fmac_f32_e32 v91, v14, v14
	v_add_f32_e32 v90, v90, v91
	v_mul_f32_e32 v91, v9, v9
	v_mul_f32_e32 v100, v11, v11
	v_fmac_f32_e32 v91, v8, v8
	v_fmac_f32_e32 v100, v10, v10
	v_add_f32_e32 v91, v91, v100
	v_add_f32_e32 v90, v90, v91
	v_mul_f32_e32 v91, v5, v5
	v_mul_f32_e32 v100, v7, v7
	v_fmac_f32_e32 v91, v4, v4
	v_fmac_f32_e32 v100, v6, v6
	v_add_f32_e32 v91, v91, v100
	v_add_f32_e32 v90, v90, v91
	v_mul_f32_e32 v91, v1, v1
	v_mul_f32_e32 v100, v3, v3
	v_fmac_f32_e32 v91, v0, v0
	v_fmac_f32_e32 v100, v2, v2
	v_add_f32_e32 v91, v91, v100
	v_add_f32_e32 v90, v90, v91
	s_nop 1
	v_mov_b32_e32 v91, v90
	s_nop 1
	v_permlane16_swap_b32_e32 v91, v90
	s_waitcnt lgkmcnt(0)
	v_add_f32_e32 v90, v90, v91
	s_nop 1
	v_mov_b32_e32 v91, v90
	s_nop 1
	v_permlane32_swap_b32_e32 v91, v90
	s_and_saveexec_b64 s[2:3], s[38:39]
	s_cbranch_execz .LBB0_673
	s_waitcnt lgkmcnt(0)
	v_add_f32_e32 v90, v90, v91
	ds_write_b32 v89, v90 offset:2816

.LBB0_703:
	v_pk_mul_f32 v[140:141], v[140:141], v[140:141]
	v_pk_mul_f32 v[142:143], v[142:143], v[142:143]
	v_pk_mul_f32 v[148:149], v[148:149], v[148:149]
	v_add_f32_e32 v142, v142, v143
	v_add_f32_e32 v140, v140, v141
	v_pk_mul_f32 v[150:151], v[150:151], v[150:151]
	v_add_f32_e32 v140, v140, v142
	v_add_f32_e32 v141, v148, v149
	v_pk_mul_f32 v[160:161], v[160:161], v[160:161]
	v_pk_mul_f32 v[162:163], v[162:163], v[162:163]
	v_add_f32_e32 v140, v141, v140
	v_add_f32_e32 v141, v150, v151
	v_pk_mul_f32 v[164:165], v[164:165], v[164:165]
	v_add_f32_e32 v140, v141, v140
	v_add_f32_e32 v141, v162, v163
	v_add_f32_e32 v142, v160, v161
	v_pk_mul_f32 v[166:167], v[166:167], v[166:167]
	v_add_f32_e32 v141, v142, v141
	v_add_f32_e32 v142, v164, v165
	v_add_f32_e32 v141, v142, v141
	v_add_f32_e32 v142, v166, v167
	v_add_f32_e32 v141, v142, v141
	v_add_f32_e32 v140, v141, v140
	s_nop 1
	v_mov_b32_e32 v141, v140
	s_nop 1
	v_permlane16_swap_b32_e32 v141, v140
	s_waitcnt lgkmcnt(0)
	v_add_f32_e32 v140, v140, v141
	s_nop 1
	v_mov_b32_e32 v141, v140
	s_nop 1
	v_permlane32_swap_b32_e32 v141, v140
	s_and_saveexec_b64 s[2:3], s[38:39]
	s_cbranch_execz .LBB0_705
	v_lshl_add_u32 v142, v236, 4, s90
	s_waitcnt lgkmcnt(0)
	v_add_f32_e32 v140, v140, v141
	ds_write_b32 v142, v140

.LBB0_713:
	v_pk_mul_f32 v[104:105], v[104:105], v[104:105]
	v_pk_mul_f32 v[106:107], v[106:107], v[106:107]
	v_pk_mul_f32 v[108:109], v[108:109], v[108:109]
	v_add_f32_e32 v106, v106, v107
	v_add_f32_e32 v104, v104, v105
	v_pk_mul_f32 v[110:111], v[110:111], v[110:111]
	v_add_f32_e32 v104, v104, v106
	v_add_f32_e32 v105, v108, v109
	v_pk_mul_f32 v[116:117], v[116:117], v[116:117]
	v_pk_mul_f32 v[118:119], v[118:119], v[118:119]
	v_add_f32_e32 v104, v105, v104
	v_add_f32_e32 v105, v110, v111
	v_pk_mul_f32 v[120:121], v[120:121], v[120:121]
	v_add_f32_e32 v104, v105, v104
	v_add_f32_e32 v105, v118, v119
	v_add_f32_e32 v106, v116, v117
	v_pk_mul_f32 v[122:123], v[122:123], v[122:123]
	v_add_f32_e32 v105, v106, v105
	v_add_f32_e32 v106, v120, v121
	v_add_f32_e32 v105, v106, v105
	v_add_f32_e32 v106, v122, v123
	v_add_f32_e32 v105, v106, v105
	v_add_f32_e32 v104, v105, v104
	s_nop 1
	v_mov_b32_e32 v105, v104
	s_nop 1
	v_permlane16_swap_b32_e32 v105, v104
	s_waitcnt lgkmcnt(0)
	v_add_f32_e32 v104, v104, v105
	s_nop 1
	v_mov_b32_e32 v105, v104
	s_nop 1
	v_permlane32_swap_b32_e32 v105, v104
	s_and_saveexec_b64 s[2:3], s[38:39]
	s_cbranch_execz .LBB0_715
	v_lshl_add_u32 v106, v140, 4, s90
	s_waitcnt lgkmcnt(0)
	v_add_f32_e32 v104, v104, v105
	ds_write_b32 v106, v104

.LBB0_723:
	v_pk_mul_f32 v[80:81], v[80:81], v[80:81]
	v_pk_mul_f32 v[82:83], v[82:83], v[82:83]
	v_pk_mul_f32 v[84:85], v[84:85], v[84:85]
	v_add_f32_e32 v82, v82, v83
	v_add_f32_e32 v80, v80, v81
	v_pk_mul_f32 v[86:87], v[86:87], v[86:87]
	v_add_f32_e32 v80, v80, v82
	v_add_f32_e32 v81, v84, v85
	v_pk_mul_f32 v[92:93], v[92:93], v[92:93]
	v_pk_mul_f32 v[94:95], v[94:95], v[94:95]
	v_add_f32_e32 v80, v81, v80
	v_add_f32_e32 v81, v86, v87
	v_pk_mul_f32 v[96:97], v[96:97], v[96:97]
	v_add_f32_e32 v80, v81, v80
	v_add_f32_e32 v81, v94, v95
	v_add_f32_e32 v82, v92, v93
	v_pk_mul_f32 v[98:99], v[98:99], v[98:99]
	v_add_f32_e32 v81, v82, v81
	v_add_f32_e32 v82, v96, v97
	v_add_f32_e32 v81, v82, v81
	v_add_f32_e32 v82, v98, v99
	v_add_f32_e32 v81, v82, v81
	v_add_f32_e32 v80, v81, v80
	s_nop 1
	v_mov_b32_e32 v81, v80
	s_nop 1
	v_permlane16_swap_b32_e32 v81, v80
	s_waitcnt lgkmcnt(0)
	v_add_f32_e32 v80, v80, v81
	s_nop 1
	v_mov_b32_e32 v81, v80
	s_nop 1
	v_permlane32_swap_b32_e32 v81, v80
	s_and_saveexec_b64 s[2:3], s[38:39]
	s_cbranch_execz .LBB0_725
	v_lshl_add_u32 v82, v104, 4, s90
	s_waitcnt lgkmcnt(0)
	v_add_f32_e32 v80, v80, v81
	ds_write_b32 v82, v80

.LBB0_733:
	v_pk_mul_f32 v[64:65], v[64:65], v[64:65]
	v_pk_mul_f32 v[66:67], v[66:67], v[66:67]
	v_pk_mul_f32 v[68:69], v[68:69], v[68:69]
	v_add_f32_e32 v66, v66, v67
	v_add_f32_e32 v64, v64, v65
	v_pk_mul_f32 v[70:71], v[70:71], v[70:71]
	v_add_f32_e32 v64, v64, v66
	v_add_f32_e32 v65, v68, v69
	v_pk_mul_f32 v[72:73], v[72:73], v[72:73]
	v_pk_mul_f32 v[74:75], v[74:75], v[74:75]
	v_add_f32_e32 v64, v65, v64
	v_add_f32_e32 v65, v70, v71
	v_pk_mul_f32 v[76:77], v[76:77], v[76:77]
	v_add_f32_e32 v64, v65, v64
	v_add_f32_e32 v65, v74, v75
	v_add_f32_e32 v66, v72, v73
	v_pk_mul_f32 v[78:79], v[78:79], v[78:79]
	v_add_f32_e32 v65, v66, v65
	v_add_f32_e32 v66, v76, v77
	v_add_f32_e32 v65, v66, v65
	v_add_f32_e32 v66, v78, v79
	v_add_f32_e32 v65, v66, v65
	v_add_f32_e32 v64, v65, v64
	s_nop 1
	v_mov_b32_e32 v65, v64
	s_nop 1
	v_permlane16_swap_b32_e32 v65, v64
	s_waitcnt lgkmcnt(0)
	v_add_f32_e32 v64, v64, v65
	s_nop 1
	v_mov_b32_e32 v65, v64
	s_nop 1
	v_permlane32_swap_b32_e32 v65, v64
	s_and_saveexec_b64 s[2:3], s[38:39]
	s_cbranch_execz .LBB0_735
	v_lshl_add_u32 v66, v80, 4, s90
	s_waitcnt lgkmcnt(0)
	v_add_f32_e32 v64, v64, v65
	ds_write_b32 v66, v64

.LBB0_743:
	v_pk_mul_f32 v[48:49], v[48:49], v[48:49]
	v_pk_mul_f32 v[50:51], v[50:51], v[50:51]
	v_pk_mul_f32 v[52:53], v[52:53], v[52:53]
	v_add_f32_e32 v50, v50, v51
	v_add_f32_e32 v48, v48, v49
	v_pk_mul_f32 v[54:55], v[54:55], v[54:55]
	v_add_f32_e32 v48, v48, v50
	v_add_f32_e32 v49, v52, v53
	v_pk_mul_f32 v[56:57], v[56:57], v[56:57]
	v_pk_mul_f32 v[58:59], v[58:59], v[58:59]
	v_add_f32_e32 v48, v49, v48
	v_add_f32_e32 v49, v54, v55
	v_pk_mul_f32 v[60:61], v[60:61], v[60:61]
	v_add_f32_e32 v48, v49, v48
	v_add_f32_e32 v49, v58, v59
	v_add_f32_e32 v50, v56, v57
	v_pk_mul_f32 v[62:63], v[62:63], v[62:63]
	v_add_f32_e32 v49, v50, v49
	v_add_f32_e32 v50, v60, v61
	v_add_f32_e32 v49, v50, v49
	v_add_f32_e32 v50, v62, v63
	v_add_f32_e32 v49, v50, v49
	v_add_f32_e32 v48, v49, v48
	s_nop 1
	v_mov_b32_e32 v49, v48
	s_nop 1
	v_permlane16_swap_b32_e32 v49, v48
	s_waitcnt lgkmcnt(0)
	v_add_f32_e32 v48, v48, v49
	s_nop 1
	v_mov_b32_e32 v49, v48
	s_nop 1
	v_permlane32_swap_b32_e32 v49, v48
	s_and_saveexec_b64 s[2:3], s[38:39]
	s_cbranch_execz .LBB0_745
	v_lshl_add_u32 v50, v64, 4, s90
	s_waitcnt lgkmcnt(0)
	v_add_f32_e32 v48, v48, v49
	ds_write_b32 v50, v48

.LBB0_753:
	v_pk_mul_f32 v[32:33], v[32:33], v[32:33]
	v_pk_mul_f32 v[34:35], v[34:35], v[34:35]
	v_pk_mul_f32 v[36:37], v[36:37], v[36:37]
	v_add_f32_e32 v34, v34, v35
	v_add_f32_e32 v32, v32, v33
	v_pk_mul_f32 v[38:39], v[38:39], v[38:39]
	v_add_f32_e32 v32, v32, v34
	v_add_f32_e32 v33, v36, v37
	v_pk_mul_f32 v[40:41], v[40:41], v[40:41]
	v_pk_mul_f32 v[42:43], v[42:43], v[42:43]
	v_add_f32_e32 v32, v33, v32
	v_add_f32_e32 v33, v38, v39
	v_pk_mul_f32 v[44:45], v[44:45], v[44:45]
	v_add_f32_e32 v32, v33, v32
	v_add_f32_e32 v33, v42, v43
	v_add_f32_e32 v34, v40, v41
	v_pk_mul_f32 v[46:47], v[46:47], v[46:47]
	v_add_f32_e32 v33, v34, v33
	v_add_f32_e32 v34, v44, v45
	v_add_f32_e32 v33, v34, v33
	v_add_f32_e32 v34, v46, v47
	v_add_f32_e32 v33, v34, v33
	v_add_f32_e32 v32, v33, v32
	s_nop 1
	v_mov_b32_e32 v33, v32
	s_nop 1
	v_permlane16_swap_b32_e32 v33, v32
	s_waitcnt lgkmcnt(0)
	v_add_f32_e32 v32, v32, v33
	s_nop 1
	v_mov_b32_e32 v33, v32
	s_nop 1
	v_permlane32_swap_b32_e32 v33, v32
	s_and_saveexec_b64 s[2:3], s[38:39]
	s_cbranch_execz .LBB0_755
	v_lshl_add_u32 v34, v48, 4, s90
	s_waitcnt lgkmcnt(0)
	v_add_f32_e32 v32, v32, v33
	ds_write_b32 v34, v32

.LBB0_763:
	v_pk_mul_f32 v[16:17], v[16:17], v[16:17]
	v_pk_mul_f32 v[18:19], v[18:19], v[18:19]
	v_pk_mul_f32 v[20:21], v[20:21], v[20:21]
	v_add_f32_e32 v18, v18, v19
	v_add_f32_e32 v16, v16, v17
	v_pk_mul_f32 v[22:23], v[22:23], v[22:23]
	v_add_f32_e32 v16, v16, v18
	v_add_f32_e32 v17, v20, v21
	v_pk_mul_f32 v[24:25], v[24:25], v[24:25]
	v_pk_mul_f32 v[26:27], v[26:27], v[26:27]
	v_add_f32_e32 v16, v17, v16
	v_add_f32_e32 v17, v22, v23
	v_pk_mul_f32 v[28:29], v[28:29], v[28:29]
	v_add_f32_e32 v16, v17, v16
	v_add_f32_e32 v17, v26, v27
	v_add_f32_e32 v18, v24, v25
	v_pk_mul_f32 v[30:31], v[30:31], v[30:31]
	v_add_f32_e32 v17, v18, v17
	v_add_f32_e32 v18, v28, v29
	v_add_f32_e32 v17, v18, v17
	v_add_f32_e32 v18, v30, v31
	v_add_f32_e32 v17, v18, v17
	v_add_f32_e32 v16, v17, v16
	s_nop 1
	v_mov_b32_e32 v17, v16
	s_nop 1
	v_permlane16_swap_b32_e32 v17, v16
	s_waitcnt lgkmcnt(0)
	v_add_f32_e32 v16, v16, v17
	s_nop 1
	v_mov_b32_e32 v17, v16
	s_nop 1
	v_permlane32_swap_b32_e32 v17, v16
	s_and_saveexec_b64 s[2:3], s[38:39]
	s_cbranch_execz .LBB0_765
	v_lshl_add_u32 v18, v32, 4, s90
	s_waitcnt lgkmcnt(0)
	v_add_f32_e32 v16, v16, v17
	ds_write_b32 v18, v16

.LBB0_773:
	v_pk_mul_f32 v[0:1], v[0:1], v[0:1]
	v_pk_mul_f32 v[2:3], v[2:3], v[2:3]
	v_pk_mul_f32 v[4:5], v[4:5], v[4:5]
	v_add_f32_e32 v2, v2, v3
	v_add_f32_e32 v0, v0, v1
	v_pk_mul_f32 v[6:7], v[6:7], v[6:7]
	v_add_f32_e32 v0, v0, v2
	v_add_f32_e32 v1, v4, v5
	v_pk_mul_f32 v[8:9], v[8:9], v[8:9]
	v_pk_mul_f32 v[10:11], v[10:11], v[10:11]
	v_add_f32_e32 v0, v1, v0
	v_add_f32_e32 v1, v6, v7
	v_pk_mul_f32 v[12:13], v[12:13], v[12:13]
	v_add_f32_e32 v0, v1, v0
	v_add_f32_e32 v1, v10, v11
	v_add_f32_e32 v2, v8, v9
	v_pk_mul_f32 v[14:15], v[14:15], v[14:15]
	v_add_f32_e32 v1, v2, v1
	v_add_f32_e32 v2, v12, v13
	v_add_f32_e32 v1, v2, v1
	v_add_f32_e32 v2, v14, v15
	v_add_f32_e32 v1, v2, v1
	v_add_f32_e32 v0, v1, v0
	s_nop 1
	v_mov_b32_e32 v1, v0
	s_nop 1
	v_permlane16_swap_b32_e32 v1, v0
	s_waitcnt lgkmcnt(0)
	v_add_f32_e32 v0, v0, v1
	s_nop 1
	v_mov_b32_e32 v1, v0
	s_nop 1
	v_permlane32_swap_b32_e32 v1, v0
	s_and_saveexec_b64 s[2:3], s[38:39]
	s_cbranch_execz .LBB0_775
	v_lshl_add_u32 v2, v16, 4, s90
	s_waitcnt lgkmcnt(0)
	v_add_f32_e32 v0, v0, v1
	ds_write_b32 v2, v0
